# MLA tile loop hand-rewritten: 32-key software pipeline, LDS-DMA staging, -m folded in QK acc init
# speedup vs baseline: 1.0174x; 1.0174x over previous
; #define PG8_STAGE(bufoff, gbase, voff) do { _Pragma("unroll") for (int _i = 0; _i < 2; ++_i) \
;     __builtin_amdgcn_global_load_lds((const unsigned*)((const char*)(gbase) + (voff)[_i]), (LAS unsigned*)(lds + (bufoff) + ldsw + _i * 8192), 16, 0, 0); } while (0)
; #define PG8_LDA(dst, b, h) do { _Pragma("unroll") for (int m = 0; m < 4; ++m) _Pragma("unroll") for (int k = 0; k < 2; ++k) dst[m][k] = *(const LAS bf16x8*)(lds + PG8_SA(b, h) + aoff + m * 2048 + k * 1024); } while (0)
; #define PG8_LDB(dst, b, h) do { _Pragma("unroll") for (int n = 0; n < 2; ++n) _Pragma("unroll") for (int k = 0; k < 2; ++k) dst[n][k] = *(const LAS bf16x8*)(lds + PG8_SB(b, h) + boff + n * 2048 + k * 1024); } while (0)
; #define PG8_MMA(ai, bj, At, Bt) do { __builtin_amdgcn_s_setprio(1); _Pragma("unroll") for (int m = 0; m < 4; ++m) _Pragma("unroll") for (int n = 0; n < 2; ++n) _Pragma("unroll") for (int k = 0; k < 2; ++k) \
;     acc[ai][bj][m][n] = __builtin_amdgcn_mfma_f32_16x16x32_bf16(Bt[n][k], At[m][k], acc[ai][bj][m][n], 0, 0, 0); __builtin_amdgcn_s_setprio(0); } while (0)
; #define PG8_WAIT_L(n) asm volatile("s_waitcnt lgkmcnt(" #n ")" ::: "memory")
; #define PG8_BAR __builtin_amdgcn_s_barrier()
; #define PG8_SCHED __builtin_amdgcn_sched_barrier(0)
; template <class Epi>
; __device__ __forceinline__ void gemm_phase(LAS unsigned char* lds, const Gemm g, const StaticOrder& S, const Epi& E, int wv0) {
;     ...
;     for (int t = 0; t < nt; t += 2) {
;       const bool last = (t == nt - 2);
;       const char* a1 = cA + (size_t)(t + 1) * kstep;
;       const char* a2 = last ? nA : cA + (size_t)(t + 2) * kstep; const char* b2 = last ? nB : cB + (size_t)(t + 2) * kstep;
;       const char* a3 = a2 + kstep; const char* b3 = b2 + kstep;
;       PG8_LDB(B0, 0, 0); PG8_SCHED; PG8_LDA(At, 0, 0); PG8_STAGE(PG8_SA(1, 1), a1 + hstepA, voffA);
;       PG8_WAIT_L(8); PG8_BAR; PG8_WAIT_L(0); PG8_MMA(0, 0, At, B0); PG8_BAR; PG8_SCHED;
;       PG8_LDB(B1, 0, 1); PG8_STAGE(PG8_SB(0, 0), b2, voffB);
;       PG8_BAR; PG8_WAIT_L(0); PG8_MMA(0, 1, At, B1); PG8_BAR;
;       PG8_LDA(At, 0, 1); PG8_STAGE(PG8_SA(0, 0), a2, voffA);
;       PG8_BAR; PG8_WAIT_L(0); PG8_MMA(1, 0, At, B0); PG8_BAR; PG8_SCHED;
.LBB0_153:
	s_add_u32 s0, s8, 0xfff80080
	s_addc_u32 s24, s9, -1
	s_add_i32 s49, 0, 0x10000
	v_add_u32_e32 v96, s49, v196
	s_waitcnt vmcnt(6)
	ds_read_b128 v[88:91], v96
	ds_read_b128 v[92:95], v96 offset:1024
	ds_read_b128 v[106:109], v96 offset:2048
	ds_read_b128 v[110:113], v96 offset:3072
	s_cmp_eq_u32 s29, 28
	s_cselect_b32 s27, s1, s24
	s_cselect_b32 s26, s5, s0
	s_cselect_b32 s25, s7, s28
	s_cselect_b32 s24, s17, s19
	v_lshl_add_u64 v[190:191], s[8:9], 0, v[170:171]
	s_add_i32 m0, s39, 0xc000
	ds_read_b128 v[122:125], v197
	ds_read_b128 v[126:129], v197 offset:1024
	ds_read_b128 v[138:141], v197 offset:2048
	ds_read_b128 v[142:145], v197 offset:3072
	ds_read_b128 v[174:177], v197 offset:4096
	ds_read_b128 v[178:181], v197 offset:5120
	ds_read_b128 v[182:185], v197 offset:6144
	ds_read_b128 v[186:189], v197 offset:7168
	global_load_lds_dwordx4 v[190:191], off
	v_lshl_add_u64 v[190:191], s[8:9], 0, v[172:173]
	s_add_i32 m0, s39, 0xe000
	s_nop 0
	global_load_lds_dwordx4 v[190:191], off
	s_waitcnt lgkmcnt(8)
	s_barrier
	s_waitcnt lgkmcnt(0)
	s_setprio 1
	s_waitcnt lgkmcnt(0)
	v_mfma_f32_16x16x32_bf16 v[68:71], v[88:91], v[122:125], v[68:71]
	v_mfma_f32_16x16x32_bf16 v[64:67], v[106:109], v[122:125], v[64:67]
	v_mfma_f32_16x16x32_bf16 v[158:161], v[88:91], v[138:141], v[158:161]
	v_mfma_f32_16x16x32_bf16 v[154:157], v[106:109], v[138:141], v[154:157]
	v_mfma_f32_16x16x32_bf16 v[150:153], v[88:91], v[174:177], v[150:153]
	v_mfma_f32_16x16x32_bf16 v[146:149], v[106:109], v[174:177], v[146:149]
	v_mfma_f32_16x16x32_bf16 v[134:137], v[88:91], v[182:185], v[134:137]
	v_mfma_f32_16x16x32_bf16 v[130:133], v[106:109], v[182:185], v[130:133]
	v_mfma_f32_16x16x32_bf16 v[68:71], v[92:95], v[126:129], v[68:71]
	v_mfma_f32_16x16x32_bf16 v[64:67], v[110:113], v[126:129], v[64:67]
	v_mfma_f32_16x16x32_bf16 v[158:161], v[92:95], v[142:145], v[158:161]
	v_mfma_f32_16x16x32_bf16 v[154:157], v[110:113], v[142:145], v[154:157]
	v_mfma_f32_16x16x32_bf16 v[150:153], v[92:95], v[178:181], v[150:153]
	v_mfma_f32_16x16x32_bf16 v[146:149], v[110:113], v[178:181], v[146:149]
	v_mfma_f32_16x16x32_bf16 v[134:137], v[92:95], v[186:189], v[134:137]
	v_mfma_f32_16x16x32_bf16 v[130:133], v[110:113], v[186:189], v[130:133]
	s_setprio 0
	s_barrier
	s_add_i32 s0, 0, 0x14000
	s_add_i32 s49, s49, s38
	v_add_u32_e32 v96, s0, v196
	v_lshl_add_u64 v[210:211], s[24:25], 0, v[164:165]
	s_mov_b32 m0, s49
	ds_read_b128 v[190:193], v96
	ds_read_b128 v[198:201], v96 offset:1024
	ds_read_b128 v[202:205], v96 offset:2048
	ds_read_b128 v[206:209], v96 offset:3072
	global_load_lds_dwordx4 v[210:211], off
	v_lshl_add_u64 v[212:213], s[24:25], 0, v[168:169]
	s_add_i32 m0, s49, 0x2000
	s_nop 0
	global_load_lds_dwordx4 v[212:213], off
	s_barrier
	s_waitcnt lgkmcnt(0)
	s_setprio 1
	s_waitcnt lgkmcnt(0)
	v_mfma_f32_16x16x32_bf16 v[56:59], v[190:193], v[122:125], v[56:59]
	v_mfma_f32_16x16x32_bf16 v[60:63], v[202:205], v[122:125], v[60:63]
	v_mfma_f32_16x16x32_bf16 v[48:51], v[190:193], v[138:141], v[48:51]
	v_mfma_f32_16x16x32_bf16 v[52:55], v[202:205], v[138:141], v[52:55]
	v_mfma_f32_16x16x32_bf16 v[40:43], v[190:193], v[174:177], v[40:43]
	v_mfma_f32_16x16x32_bf16 v[44:47], v[202:205], v[174:177], v[44:47]
	v_mfma_f32_16x16x32_bf16 v[32:35], v[190:193], v[182:185], v[32:35]
	v_mfma_f32_16x16x32_bf16 v[36:39], v[202:205], v[182:185], v[36:39]
	v_mfma_f32_16x16x32_bf16 v[56:59], v[198:201], v[126:129], v[56:59]
	v_mfma_f32_16x16x32_bf16 v[60:63], v[206:209], v[126:129], v[60:63]
	v_mfma_f32_16x16x32_bf16 v[48:51], v[198:201], v[142:145], v[48:51]
	v_mfma_f32_16x16x32_bf16 v[52:55], v[206:209], v[142:145], v[52:55]
	v_mfma_f32_16x16x32_bf16 v[40:43], v[198:201], v[178:181], v[40:43]
	v_mfma_f32_16x16x32_bf16 v[44:47], v[206:209], v[178:181], v[44:47]
	v_mfma_f32_16x16x32_bf16 v[32:35], v[198:201], v[186:189], v[32:35]
	v_mfma_f32_16x16x32_bf16 v[36:39], v[206:209], v[186:189], v[36:39]
	s_setprio 0
	s_mov_b32 m0, s39
	v_lshl_add_u64 v[214:215], s[26:27], 0, v[162:163]
	s_barrier
	ds_read_b128 v[122:125], v197 offset:16384
	ds_read_b128 v[126:129], v197 offset:17408
	ds_read_b128 v[138:141], v197 offset:18432
	ds_read_b128 v[142:145], v197 offset:19456
	ds_read_b128 v[174:177], v197 offset:20480
	ds_read_b128 v[178:181], v197 offset:21504
	ds_read_b128 v[182:185], v197 offset:22528
	ds_read_b128 v[186:189], v197 offset:23552
	global_load_lds_dwordx4 v[214:215], off
	v_lshl_add_u64 v[216:217], s[26:27], 0, v[166:167]
	s_mov_b32 m0, s40
	s_nop 0
	global_load_lds_dwordx4 v[216:217], off
	s_barrier
	s_waitcnt lgkmcnt(0)
	s_setprio 1
	s_waitcnt lgkmcnt(0)
	v_mfma_f32_16x16x32_bf16 v[118:121], v[88:91], v[122:125], v[118:121]
	v_mfma_f32_16x16x32_bf16 v[114:117], v[106:109], v[122:125], v[114:117]
	v_mfma_f32_16x16x32_bf16 v[102:105], v[88:91], v[138:141], v[102:105]
	v_mfma_f32_16x16x32_bf16 v[98:101], v[106:109], v[138:141], v[98:101]
	v_mfma_f32_16x16x32_bf16 v[84:87], v[88:91], v[174:177], v[84:87]
	v_mfma_f32_16x16x32_bf16 v[80:83], v[106:109], v[174:177], v[80:83]
	v_mfma_f32_16x16x32_bf16 v[76:79], v[88:91], v[182:185], v[76:79]
	v_mfma_f32_16x16x32_bf16 v[72:75], v[106:109], v[182:185], v[72:75]
	v_mfma_f32_16x16x32_bf16 v[118:121], v[92:95], v[126:129], v[118:121]
	v_mfma_f32_16x16x32_bf16 v[114:117], v[110:113], v[126:129], v[114:117]
	v_mfma_f32_16x16x32_bf16 v[102:105], v[92:95], v[142:145], v[102:105]
	v_mfma_f32_16x16x32_bf16 v[98:101], v[110:113], v[142:145], v[98:101]
	v_mfma_f32_16x16x32_bf16 v[84:87], v[92:95], v[178:181], v[84:87]
	v_mfma_f32_16x16x32_bf16 v[80:83], v[110:113], v[178:181], v[80:83]
	v_mfma_f32_16x16x32_bf16 v[76:79], v[92:95], v[186:189], v[76:79]
	v_mfma_f32_16x16x32_bf16 v[72:75], v[110:113], v[186:189], v[72:75]
	s_setprio 0
	s_barrier
; #define PG8_STAGE(bufoff, gbase, voff) do { _Pragma("unroll") for (int _i = 0; _i < 2; ++_i) \
;     __builtin_amdgcn_global_load_lds((const unsigned*)((const char*)(gbase) + (voff)[_i]), (LAS unsigned*)(lds + (bufoff) + ldsw + _i * 8192), 16, 0, 0); } while (0)
; #define PG8_LDA(dst, b, h) do { _Pragma("unroll") for (int m = 0; m < 4; ++m) _Pragma("unroll") for (int k = 0; k < 2; ++k) dst[m][k] = *(const LAS bf16x8*)(lds + PG8_SA(b, h) + aoff + m * 2048 + k * 1024); } while (0)
; #define PG8_LDB(dst, b, h) do { _Pragma("unroll") for (int n = 0; n < 2; ++n) _Pragma("unroll") for (int k = 0; k < 2; ++k) dst[n][k] = *(const LAS bf16x8*)(lds + PG8_SB(b, h) + boff + n * 2048 + k * 1024); } while (0)
; #define PG8_MMA(ai, bj, At, Bt) do { __builtin_amdgcn_s_setprio(1); _Pragma("unroll") for (int m = 0; m < 4; ++m) _Pragma("unroll") for (int n = 0; n < 2; ++n) _Pragma("unroll") for (int k = 0; k < 2; ++k) \
;     acc[ai][bj][m][n] = __builtin_amdgcn_mfma_f32_16x16x32_bf16(Bt[n][k], At[m][k], acc[ai][bj][m][n], 0, 0, 0); __builtin_amdgcn_s_setprio(0); } while (0)
; #define PG8_WAIT_V(n) asm volatile("s_waitcnt vmcnt(" #n ")" ::: "memory")
; #define PG8_WAIT_L(n) asm volatile("s_waitcnt lgkmcnt(" #n ")" ::: "memory")
; #define PG8_BAR __builtin_amdgcn_s_barrier()
; #define PG8_SCHED __builtin_amdgcn_sched_barrier(0)
; template <class Epi>
; __device__ __forceinline__ void gemm_phase(LAS unsigned char* lds, const Gemm g, const StaticOrder& S, const Epi& E, int wv0) {
;     ...
;       PG8_STAGE(PG8_SB(0, 1), b2 + hstepB, voffB);
;       PG8_WAIT_V(6); PG8_BAR; PG8_MMA(1, 1, At, B1); PG8_BAR;
;       PG8_LDB(B0, 1, 0); PG8_SCHED; PG8_LDA(At, 1, 0); PG8_STAGE(PG8_SA(0, 1), a2 + hstepA, voffA);
;       PG8_WAIT_L(8); PG8_BAR; PG8_WAIT_L(0); PG8_MMA(0, 0, At, B0); PG8_BAR; PG8_SCHED;
;       PG8_LDB(B1, 1, 1); PG8_STAGE(PG8_SB(1, 0), b3, voffB);
;       PG8_BAR; PG8_WAIT_L(0); PG8_MMA(0, 1, At, B1); PG8_BAR;
	s_add_u32 s50, s24, 0x80000
	s_addc_u32 s51, s25, 0
	s_add_i32 s0, s0, s38
	v_lshl_add_u64 v[88:89], s[50:51], 0, v[164:165]
	s_mov_b32 m0, s0
	s_nop 0
	global_load_lds_dwordx4 v[88:89], off
	v_lshl_add_u64 v[88:89], s[50:51], 0, v[168:169]
	s_add_i32 m0, s0, 0x2000
	s_nop 0
	global_load_lds_dwordx4 v[88:89], off
	s_waitcnt vmcnt(6)
	s_barrier
	s_setprio 1
	v_mfma_f32_16x16x32_bf16 v[24:27], v[190:193], v[122:125], v[24:27]
	v_mfma_f32_16x16x32_bf16 v[28:31], v[202:205], v[122:125], v[28:31]
	v_mfma_f32_16x16x32_bf16 v[16:19], v[190:193], v[138:141], v[16:19]
	v_mfma_f32_16x16x32_bf16 v[20:23], v[202:205], v[138:141], v[20:23]
	v_mfma_f32_16x16x32_bf16 v[8:11], v[190:193], v[174:177], v[8:11]
	v_mfma_f32_16x16x32_bf16 v[12:15], v[202:205], v[174:177], v[12:15]
	v_mfma_f32_16x16x32_bf16 v[0:3], v[190:193], v[182:185], v[0:3]
	v_mfma_f32_16x16x32_bf16 v[4:7], v[202:205], v[182:185], v[4:7]
	v_mfma_f32_16x16x32_bf16 v[24:27], v[198:201], v[126:129], v[24:27]
	v_mfma_f32_16x16x32_bf16 v[28:31], v[206:209], v[126:129], v[28:31]
	v_mfma_f32_16x16x32_bf16 v[16:19], v[198:201], v[142:145], v[16:19]
	v_mfma_f32_16x16x32_bf16 v[20:23], v[206:209], v[142:145], v[20:23]
	v_mfma_f32_16x16x32_bf16 v[8:11], v[198:201], v[178:181], v[8:11]
	v_mfma_f32_16x16x32_bf16 v[12:15], v[206:209], v[178:181], v[12:15]
	v_mfma_f32_16x16x32_bf16 v[0:3], v[198:201], v[186:189], v[0:3]
	v_mfma_f32_16x16x32_bf16 v[4:7], v[206:209], v[186:189], v[4:7]
	s_setprio 0
	s_add_i32 s0, 0, 0x18000
	v_add_u32_e32 v96, s0, v196
	s_barrier
	ds_read_b128 v[88:91], v96
	ds_read_b128 v[92:95], v96 offset:1024
	ds_read_b128 v[106:109], v96 offset:2048
	ds_read_b128 v[110:113], v96 offset:3072
	s_add_u32 s26, s26, 0x80000
	s_addc_u32 s27, s27, 0
	s_mov_b32 m0, s41
	v_lshl_add_u64 v[190:191], s[26:27], 0, v[162:163]
	ds_read_b128 v[122:125], v197 offset:32768
	ds_read_b128 v[126:129], v197 offset:33792
	ds_read_b128 v[138:141], v197 offset:34816
	ds_read_b128 v[142:145], v197 offset:35840
	ds_read_b128 v[174:177], v197 offset:36864
	ds_read_b128 v[178:181], v197 offset:37888
	ds_read_b128 v[182:185], v197 offset:38912
	ds_read_b128 v[186:189], v197 offset:39936
	global_load_lds_dwordx4 v[190:191], off
	v_lshl_add_u64 v[190:191], s[26:27], 0, v[166:167]
	s_mov_b32 m0, s42
	s_nop 0
	global_load_lds_dwordx4 v[190:191], off
	s_waitcnt lgkmcnt(8)
	s_barrier
	s_waitcnt lgkmcnt(0)
	s_setprio 1
	s_waitcnt lgkmcnt(0)
	v_mfma_f32_16x16x32_bf16 v[68:71], v[88:91], v[122:125], v[68:71]
	v_mfma_f32_16x16x32_bf16 v[64:67], v[106:109], v[122:125], v[64:67]
	v_mfma_f32_16x16x32_bf16 v[158:161], v[88:91], v[138:141], v[158:161]
	v_mfma_f32_16x16x32_bf16 v[154:157], v[106:109], v[138:141], v[154:157]
	v_mfma_f32_16x16x32_bf16 v[150:153], v[88:91], v[174:177], v[150:153]
	v_mfma_f32_16x16x32_bf16 v[146:149], v[106:109], v[174:177], v[146:149]
	v_mfma_f32_16x16x32_bf16 v[134:137], v[88:91], v[182:185], v[134:137]
	v_mfma_f32_16x16x32_bf16 v[130:133], v[106:109], v[182:185], v[130:133]
	v_mfma_f32_16x16x32_bf16 v[68:71], v[92:95], v[126:129], v[68:71]
	v_mfma_f32_16x16x32_bf16 v[64:67], v[110:113], v[126:129], v[64:67]
	v_mfma_f32_16x16x32_bf16 v[158:161], v[92:95], v[142:145], v[158:161]
	v_mfma_f32_16x16x32_bf16 v[154:157], v[110:113], v[142:145], v[154:157]
	v_mfma_f32_16x16x32_bf16 v[150:153], v[92:95], v[178:181], v[150:153]
	v_mfma_f32_16x16x32_bf16 v[146:149], v[110:113], v[178:181], v[146:149]
	v_mfma_f32_16x16x32_bf16 v[134:137], v[92:95], v[186:189], v[134:137]
	v_mfma_f32_16x16x32_bf16 v[130:133], v[110:113], v[186:189], v[130:133]
	s_setprio 0
	s_barrier
	s_add_i32 s26, 0, 0x1c000
	s_add_i32 s0, s0, s38
	v_add_u32_e32 v96, s26, v196
	v_lshl_add_u64 v[210:211], v[210:211], 0, s[72:73]
	s_mov_b32 m0, s0
	ds_read_b128 v[190:193], v96
	ds_read_b128 v[198:201], v96 offset:1024
	ds_read_b128 v[202:205], v96 offset:2048
	ds_read_b128 v[206:209], v96 offset:3072
	global_load_lds_dwordx4 v[210:211], off
	v_lshl_add_u64 v[210:211], v[212:213], 0, s[72:73]
	s_add_i32 m0, s0, 0x2000
	s_nop 0
	global_load_lds_dwordx4 v[210:211], off
	s_barrier
; #define PG8_STAGE(bufoff, gbase, voff) do { _Pragma("unroll") for (int _i = 0; _i < 2; ++_i) \
;     __builtin_amdgcn_global_load_lds((const unsigned*)((const char*)(gbase) + (voff)[_i]), (LAS unsigned*)(lds + (bufoff) + ldsw + _i * 8192), 16, 0, 0); } while (0)
; #define PG8_LDA(dst, b, h) do { _Pragma("unroll") for (int m = 0; m < 4; ++m) _Pragma("unroll") for (int k = 0; k < 2; ++k) dst[m][k] = *(const LAS bf16x8*)(lds + PG8_SA(b, h) + aoff + m * 2048 + k * 1024); } while (0)
; #define PG8_MMA(ai, bj, At, Bt) do { __builtin_amdgcn_s_setprio(1); _Pragma("unroll") for (int m = 0; m < 4; ++m) _Pragma("unroll") for (int n = 0; n < 2; ++n) _Pragma("unroll") for (int k = 0; k < 2; ++k) \
;     acc[ai][bj][m][n] = __builtin_amdgcn_mfma_f32_16x16x32_bf16(Bt[n][k], At[m][k], acc[ai][bj][m][n], 0, 0, 0); __builtin_amdgcn_s_setprio(0); } while (0)
; #define PG8_WAIT_V(n) asm volatile("s_waitcnt vmcnt(" #n ")" ::: "memory")
; #define PG8_WAIT_L(n) asm volatile("s_waitcnt lgkmcnt(" #n ")" ::: "memory")
; #define PG8_BAR __builtin_amdgcn_s_barrier()
; #define PG8_SCHED __builtin_amdgcn_sched_barrier(0)
; template <class Epi>
; __device__ __forceinline__ void gemm_phase(LAS unsigned char* lds, const Gemm g, const StaticOrder& S, const Epi& E, int wv0) {
;     ...
;       PG8_BAR; PG8_WAIT_L(0); PG8_MMA(0, 1, At, B1); PG8_BAR;
;       PG8_LDA(At, 1, 1); PG8_STAGE(PG8_SA(1, 0), a3, voffA);
;       PG8_BAR; PG8_WAIT_L(0); PG8_MMA(1, 0, At, B0); PG8_BAR; PG8_SCHED;
;       PG8_STAGE(PG8_SB(1, 1), b3 + hstepB, voffB);
;       PG8_WAIT_V(6); PG8_BAR; PG8_MMA(1, 1, At, B1); PG8_BAR;
;     }
;     E(acc, cur, wr, wc, fr, fq);
;   __device__ __forceinline__ void preload(EpiPre& q, int row, int col) const {
;     ...
;       if (col >= C_KR && col < C_HU) { const float* cs = e.f0 + ((size_t)row * 32 + ((col - C_KR) >> 1)) * 2; q.a0 = *(const f32x4*)cs; q.a1 = *(const f32x4*)(cs + 4); }
	s_waitcnt lgkmcnt(0)
	s_setprio 1
	s_waitcnt lgkmcnt(0)
	v_mfma_f32_16x16x32_bf16 v[56:59], v[190:193], v[122:125], v[56:59]
	v_mfma_f32_16x16x32_bf16 v[60:63], v[202:205], v[122:125], v[60:63]
	v_mfma_f32_16x16x32_bf16 v[48:51], v[190:193], v[138:141], v[48:51]
	v_mfma_f32_16x16x32_bf16 v[52:55], v[202:205], v[138:141], v[52:55]
	v_mfma_f32_16x16x32_bf16 v[40:43], v[190:193], v[174:177], v[40:43]
	v_mfma_f32_16x16x32_bf16 v[44:47], v[202:205], v[174:177], v[44:47]
	v_mfma_f32_16x16x32_bf16 v[32:35], v[190:193], v[182:185], v[32:35]
	v_mfma_f32_16x16x32_bf16 v[36:39], v[202:205], v[182:185], v[36:39]
	v_mfma_f32_16x16x32_bf16 v[56:59], v[198:201], v[126:129], v[56:59]
	v_mfma_f32_16x16x32_bf16 v[60:63], v[206:209], v[126:129], v[60:63]
	v_mfma_f32_16x16x32_bf16 v[48:51], v[198:201], v[142:145], v[48:51]
	v_mfma_f32_16x16x32_bf16 v[52:55], v[206:209], v[142:145], v[52:55]
	v_mfma_f32_16x16x32_bf16 v[40:43], v[198:201], v[178:181], v[40:43]
	v_mfma_f32_16x16x32_bf16 v[44:47], v[206:209], v[178:181], v[44:47]
	v_mfma_f32_16x16x32_bf16 v[32:35], v[198:201], v[186:189], v[32:35]
	v_mfma_f32_16x16x32_bf16 v[36:39], v[206:209], v[186:189], v[36:39]
	s_setprio 0
	s_mov_b32 m0, s44
	v_lshl_add_u64 v[210:211], v[214:215], 0, s[72:73]
	s_barrier
	ds_read_b128 v[122:125], v197 offset:49152
	ds_read_b128 v[126:129], v197 offset:50176
	ds_read_b128 v[138:141], v197 offset:51200
	ds_read_b128 v[142:145], v197 offset:52224
	ds_read_b128 v[174:177], v197 offset:53248
	ds_read_b128 v[178:181], v197 offset:54272
	ds_read_b128 v[182:185], v197 offset:55296
	ds_read_b128 v[186:189], v197 offset:56320
	global_load_lds_dwordx4 v[210:211], off
	v_lshl_add_u64 v[210:211], v[216:217], 0, s[72:73]
	s_mov_b32 m0, s45
	s_nop 0
	global_load_lds_dwordx4 v[210:211], off
	s_barrier
	s_waitcnt lgkmcnt(0)
	s_setprio 1
	s_waitcnt lgkmcnt(0)
	v_mfma_f32_16x16x32_bf16 v[118:121], v[88:91], v[122:125], v[118:121]
	v_mfma_f32_16x16x32_bf16 v[114:117], v[106:109], v[122:125], v[114:117]
	v_mfma_f32_16x16x32_bf16 v[102:105], v[88:91], v[138:141], v[102:105]
	v_mfma_f32_16x16x32_bf16 v[98:101], v[106:109], v[138:141], v[98:101]
	v_mfma_f32_16x16x32_bf16 v[84:87], v[88:91], v[174:177], v[84:87]
	v_mfma_f32_16x16x32_bf16 v[80:83], v[106:109], v[174:177], v[80:83]
	v_mfma_f32_16x16x32_bf16 v[76:79], v[88:91], v[182:185], v[76:79]
	v_mfma_f32_16x16x32_bf16 v[72:75], v[106:109], v[182:185], v[72:75]
	v_mfma_f32_16x16x32_bf16 v[118:121], v[92:95], v[126:129], v[118:121]
	v_mfma_f32_16x16x32_bf16 v[114:117], v[110:113], v[126:129], v[114:117]
	v_mfma_f32_16x16x32_bf16 v[102:105], v[92:95], v[142:145], v[102:105]
	v_mfma_f32_16x16x32_bf16 v[98:101], v[110:113], v[142:145], v[98:101]
	v_mfma_f32_16x16x32_bf16 v[84:87], v[92:95], v[178:181], v[84:87]
	v_mfma_f32_16x16x32_bf16 v[80:83], v[110:113], v[178:181], v[80:83]
	v_mfma_f32_16x16x32_bf16 v[76:79], v[92:95], v[186:189], v[76:79]
	v_mfma_f32_16x16x32_bf16 v[72:75], v[110:113], v[186:189], v[72:75]
	s_setprio 0
	s_barrier
	s_add_u32 s24, s24, 0x80080
	s_addc_u32 s25, s25, 0
	s_add_i32 s0, s26, s38
	v_lshl_add_u64 v[88:89], s[24:25], 0, v[164:165]
	s_mov_b32 m0, s0
	s_nop 0
	global_load_lds_dwordx4 v[88:89], off
	v_lshl_add_u64 v[88:89], s[24:25], 0, v[168:169]
	s_add_i32 m0, s0, 0x2000
	s_nop 0
	global_load_lds_dwordx4 v[88:89], off
	s_waitcnt vmcnt(6)
	s_barrier
	s_setprio 1
	v_mfma_f32_16x16x32_bf16 v[24:27], v[190:193], v[122:125], v[24:27]
	v_mfma_f32_16x16x32_bf16 v[28:31], v[202:205], v[122:125], v[28:31]
	v_mfma_f32_16x16x32_bf16 v[16:19], v[190:193], v[138:141], v[16:19]
	v_mfma_f32_16x16x32_bf16 v[20:23], v[202:205], v[138:141], v[20:23]
	v_mfma_f32_16x16x32_bf16 v[8:11], v[190:193], v[174:177], v[8:11]
	v_mfma_f32_16x16x32_bf16 v[12:15], v[202:205], v[174:177], v[12:15]
	v_mfma_f32_16x16x32_bf16 v[0:3], v[190:193], v[182:185], v[0:3]
	v_mfma_f32_16x16x32_bf16 v[4:7], v[202:205], v[182:185], v[4:7]
	v_mfma_f32_16x16x32_bf16 v[24:27], v[198:201], v[126:129], v[24:27]
	v_mfma_f32_16x16x32_bf16 v[28:31], v[206:209], v[126:129], v[28:31]
	v_mfma_f32_16x16x32_bf16 v[16:19], v[198:201], v[142:145], v[16:19]
	v_mfma_f32_16x16x32_bf16 v[20:23], v[206:209], v[142:145], v[20:23]
	v_mfma_f32_16x16x32_bf16 v[8:11], v[198:201], v[178:181], v[8:11]
	v_mfma_f32_16x16x32_bf16 v[12:15], v[206:209], v[178:181], v[12:15]
	v_mfma_f32_16x16x32_bf16 v[0:3], v[198:201], v[186:189], v[0:3]
	v_mfma_f32_16x16x32_bf16 v[4:7], v[206:209], v[186:189], v[4:7]
	s_setprio 0
	s_add_i32 s29, s29, 2
	s_add_u32 s8, s8, 0x100
	s_addc_u32 s9, s9, 0
	s_add_u32 s19, s19, 0x100
	s_addc_u32 s28, s28, 0
	s_cmp_gt_u32 s29, 29
	s_barrier
	s_cbranch_scc0 .LBB0_153
	s_lshl_b32 s0, s4, 8
	s_or_b32 s17, s0, s43
	s_and_b32 s0, s17, 0xffffff40
	v_bitop3_b32 v88, s17, 56, v195 bitop3:0xc8
	v_lshlrev_b32_e32 v96, 2, v88
	s_cmpk_eq_i32 s0, 0x500
	v_lshl_add_u32 v176, s6, 8, v194
	s_cselect_b64 s[4:5], -1, 0
	s_cmpk_lg_i32 s0, 0x500
	v_lshl_add_u64 v[178:179], s[14:15], 0, v[96:97]
	s_cbranch_scc1 .LBB0_156
	v_ashrrev_i32_e32 v177, 31, v176
	v_lshlrev_b64 v[88:89], 8, v[176:177]
	v_lshl_add_u64 v[88:89], v[178:179], 0, v[88:89]
	global_load_dwordx4 v[138:141], v[88:89], off offset:16
	global_load_dwordx4 v[142:145], v[88:89], off

; #define PG8_STAGE(bufoff, gbase, voff) do { _Pragma("unroll") for (int _i = 0; _i < 2; ++_i) \
;     __builtin_amdgcn_global_load_lds((const unsigned*)((const char*)(gbase) + (voff)[_i]), (LAS unsigned*)(lds + (bufoff) + ldsw + _i * 8192), 16, 0, 0); } while (0)
; #define PG8_LDA(dst, b, h) do { _Pragma("unroll") for (int m = 0; m < 4; ++m) _Pragma("unroll") for (int k = 0; k < 2; ++k) dst[m][k] = *(const LAS bf16x8*)(lds + PG8_SA(b, h) + aoff + m * 2048 + k * 1024); } while (0)
; #define PG8_LDB(dst, b, h) do { _Pragma("unroll") for (int n = 0; n < 2; ++n) _Pragma("unroll") for (int k = 0; k < 2; ++k) dst[n][k] = *(const LAS bf16x8*)(lds + PG8_SB(b, h) + boff + n * 2048 + k * 1024); } while (0)
; #define PG8_MMA(ai, bj, At, Bt) do { __builtin_amdgcn_s_setprio(1); _Pragma("unroll") for (int m = 0; m < 4; ++m) _Pragma("unroll") for (int n = 0; n < 2; ++n) _Pragma("unroll") for (int k = 0; k < 2; ++k) \
;     acc[ai][bj][m][n] = __builtin_amdgcn_mfma_f32_16x16x32_bf16(Bt[n][k], At[m][k], acc[ai][bj][m][n], 0, 0, 0); __builtin_amdgcn_s_setprio(0); } while (0)
; #define PG8_WAIT_L(n) asm volatile("s_waitcnt lgkmcnt(" #n ")" ::: "memory")
; #define PG8_BAR __builtin_amdgcn_s_barrier()
; #define PG8_SCHED __builtin_amdgcn_sched_barrier(0)
; template <class Epi>
; __device__ __forceinline__ void gemm_phase(LAS unsigned char* lds, const Gemm g, const StaticOrder& S, const Epi& E, int wv0) {
;     ...
;     for (int t = 0; t < nt; t += 2) {
;       const bool last = (t == nt - 2);
;       const char* a1 = cA + (size_t)(t + 1) * kstep;
;       const char* a2 = last ? nA : cA + (size_t)(t + 2) * kstep; const char* b2 = last ? nB : cB + (size_t)(t + 2) * kstep;
;       const char* a3 = a2 + kstep; const char* b3 = b2 + kstep;
;       PG8_LDB(B0, 0, 0); PG8_SCHED; PG8_LDA(At, 0, 0); PG8_STAGE(PG8_SA(1, 1), a1 + hstepA, voffA);
;       PG8_WAIT_L(8); PG8_BAR; PG8_WAIT_L(0); PG8_MMA(0, 0, At, B0); PG8_BAR; PG8_SCHED;
;       PG8_LDB(B1, 0, 1); PG8_STAGE(PG8_SB(0, 0), b2, voffB);
;       PG8_BAR; PG8_WAIT_L(0); PG8_MMA(0, 1, At, B1); PG8_BAR;
;       PG8_LDA(At, 0, 1); PG8_STAGE(PG8_SA(0, 0), a2, voffA);
;       PG8_BAR; PG8_WAIT_L(0); PG8_MMA(1, 0, At, B0); PG8_BAR; PG8_SCHED;
.LBB0_671:
	s_add_u32 s4, s18, 0x100
	s_addc_u32 s5, s19, 0
	s_add_i32 s0, 0, 0x10000
	s_waitcnt vmcnt(6)
	v_add_u32_e32 v80, s0, v253
	ds_read_b128 v[72:75], v80
	ds_read_b128 v[76:79], v80 offset:1024
	ds_read_b128 v[90:93], v80 offset:2048
	ds_read_b128 v[98:101], v80 offset:3072
	s_cmp_eq_u32 s46, 4
	s_cselect_b32 s23, s13, s5
	s_cselect_b32 s22, s12, s4
	s_cselect_b32 s21, s11, s45
	s_cselect_b32 s20, s17, s44
	v_lshl_add_u64 v[80:81], s[18:19], 0, v[230:231]
	s_add_i32 m0, s34, 0xc000
	ds_read_b128 v[110:113], v244
	ds_read_b128 v[114:117], v244 offset:1024
	ds_read_b128 v[118:121], v244 offset:2048
	ds_read_b128 v[122:125], v244 offset:3072
	ds_read_b128 v[136:139], v244 offset:4096
	ds_read_b128 v[140:143], v244 offset:5120
	ds_read_b128 v[144:147], v244 offset:6144
	ds_read_b128 v[148:151], v244 offset:7168
	global_load_lds_dwordx4 v[80:81], off
	v_lshl_add_u64 v[80:81], s[18:19], 0, v[232:233]
	s_add_i32 m0, s34, 0xe000
	s_nop 0
	global_load_lds_dwordx4 v[80:81], off
	s_waitcnt lgkmcnt(8)
	s_barrier
	s_waitcnt lgkmcnt(0)
	s_setprio 1
	s_waitcnt lgkmcnt(0)
	v_mfma_f32_16x16x32_bf16 v[132:135], v[72:75], v[136:139], v[132:135]
	v_mfma_f32_16x16x32_bf16 v[126:129], v[90:93], v[136:139], v[128:131]
	v_mfma_f32_16x16x32_bf16 v[86:89], v[72:75], v[144:147], v[86:89]
	v_mfma_f32_16x16x32_bf16 v[80:83], v[90:93], v[144:147], v[82:85]
	v_mfma_f32_16x16x32_bf16 v[152:155], v[72:75], v[110:113], v[202:205]
	v_mfma_f32_16x16x32_bf16 v[156:159], v[90:93], v[110:113], v[198:201]
	v_mfma_f32_16x16x32_bf16 v[170:173], v[72:75], v[118:121], v[186:189]
	v_mfma_f32_16x16x32_bf16 v[174:177], v[90:93], v[118:121], v[182:185]
	v_mfma_f32_16x16x32_bf16 v[132:135], v[76:79], v[140:143], v[132:135]
	v_mfma_f32_16x16x32_bf16 v[126:129], v[98:101], v[140:143], v[126:129]
	v_mfma_f32_16x16x32_bf16 v[86:89], v[76:79], v[148:151], v[86:89]
	v_mfma_f32_16x16x32_bf16 v[80:83], v[98:101], v[148:151], v[80:83]
	v_mfma_f32_16x16x32_bf16 v[152:155], v[76:79], v[114:117], v[152:155]
	v_mfma_f32_16x16x32_bf16 v[156:159], v[98:101], v[114:117], v[156:159]
	v_mfma_f32_16x16x32_bf16 v[170:173], v[76:79], v[122:125], v[170:173]
	v_mfma_f32_16x16x32_bf16 v[174:177], v[98:101], v[122:125], v[174:177]
	s_setprio 0
	s_barrier
	s_add_i32 s47, 0, 0x14000
	s_add_i32 s0, s0, s31
	v_add_u32_e32 v84, s47, v253
	v_lshl_add_u64 v[214:215], s[20:21], 0, v[224:225]
	s_mov_b32 m0, s0
	ds_read_b128 v[178:181], v84
	ds_read_b128 v[182:185], v84 offset:1024
	ds_read_b128 v[186:189], v84 offset:2048
	ds_read_b128 v[198:201], v84 offset:3072
	global_load_lds_dwordx4 v[214:215], off
	v_lshl_add_u64 v[216:217], s[20:21], 0, v[228:229]
	s_add_i32 m0, s0, 0x2000
	s_nop 0
	global_load_lds_dwordx4 v[216:217], off
	s_barrier
	s_waitcnt lgkmcnt(0)
	s_setprio 1
	s_waitcnt lgkmcnt(0)
	v_mfma_f32_16x16x32_bf16 v[194:197], v[178:181], v[110:113], v[194:197]
	v_mfma_f32_16x16x32_bf16 v[110:113], v[186:189], v[110:113], v[190:193]
	v_mfma_f32_16x16x32_bf16 v[106:109], v[178:181], v[136:139], v[106:109]
	v_mfma_f32_16x16x32_bf16 v[102:105], v[186:189], v[136:139], v[102:105]
	v_mfma_f32_16x16x32_bf16 v[68:71], v[178:181], v[144:147], v[68:71]
	v_mfma_f32_16x16x32_bf16 v[64:67], v[186:189], v[144:147], v[64:67]
	v_mfma_f32_16x16x32_bf16 v[194:197], v[182:185], v[114:117], v[194:197]
	v_mfma_f32_16x16x32_bf16 v[110:113], v[198:201], v[114:117], v[110:113]
	v_mfma_f32_16x16x32_bf16 v[114:117], v[178:181], v[118:121], v[166:169]
	v_mfma_f32_16x16x32_bf16 v[118:121], v[186:189], v[118:121], v[162:165]
	v_mfma_f32_16x16x32_bf16 v[106:109], v[182:185], v[140:143], v[106:109]
	v_mfma_f32_16x16x32_bf16 v[102:105], v[198:201], v[140:143], v[102:105]
	v_mfma_f32_16x16x32_bf16 v[68:71], v[182:185], v[148:151], v[68:71]
	v_mfma_f32_16x16x32_bf16 v[64:67], v[198:201], v[148:151], v[64:67]
	v_mfma_f32_16x16x32_bf16 v[114:117], v[182:185], v[122:125], v[114:117]
	v_mfma_f32_16x16x32_bf16 v[118:121], v[198:201], v[122:125], v[118:121]
	s_setprio 0
	s_mov_b32 m0, s34
	v_lshl_add_u64 v[218:219], s[22:23], 0, v[94:95]
	s_barrier
	ds_read_b128 v[122:125], v244 offset:16384
	ds_read_b128 v[136:139], v244 offset:17408
	ds_read_b128 v[140:143], v244 offset:18432
	ds_read_b128 v[144:147], v244 offset:19456
	ds_read_b128 v[148:151], v244 offset:20480
	ds_read_b128 v[160:163], v244 offset:21504
	ds_read_b128 v[164:167], v244 offset:22528
	ds_read_b128 v[190:193], v244 offset:23552
	global_load_lds_dwordx4 v[218:219], off
	v_lshl_add_u64 v[220:221], s[22:23], 0, v[226:227]
	s_mov_b32 m0, s35
	s_nop 0
	global_load_lds_dwordx4 v[220:221], off
	s_barrier
	s_waitcnt lgkmcnt(0)
	s_setprio 1
	s_waitcnt lgkmcnt(0)
	v_mfma_f32_16x16x32_bf16 v[60:63], v[72:75], v[122:125], v[60:63]
	v_mfma_f32_16x16x32_bf16 v[56:59], v[90:93], v[122:125], v[56:59]
	v_mfma_f32_16x16x32_bf16 v[44:47], v[72:75], v[140:143], v[44:47]
	v_mfma_f32_16x16x32_bf16 v[40:43], v[90:93], v[140:143], v[40:43]
	v_mfma_f32_16x16x32_bf16 v[28:31], v[72:75], v[148:151], v[28:31]
	v_mfma_f32_16x16x32_bf16 v[24:27], v[90:93], v[148:151], v[24:27]
	v_mfma_f32_16x16x32_bf16 v[12:15], v[72:75], v[164:167], v[12:15]
	v_mfma_f32_16x16x32_bf16 v[8:11], v[90:93], v[164:167], v[8:11]
	v_mfma_f32_16x16x32_bf16 v[60:63], v[76:79], v[136:139], v[60:63]
	v_mfma_f32_16x16x32_bf16 v[56:59], v[98:101], v[136:139], v[56:59]
	v_mfma_f32_16x16x32_bf16 v[44:47], v[76:79], v[144:147], v[44:47]
	v_mfma_f32_16x16x32_bf16 v[40:43], v[98:101], v[144:147], v[40:43]
	v_mfma_f32_16x16x32_bf16 v[28:31], v[76:79], v[160:163], v[28:31]
	v_mfma_f32_16x16x32_bf16 v[24:27], v[98:101], v[160:163], v[24:27]
	v_mfma_f32_16x16x32_bf16 v[12:15], v[76:79], v[190:193], v[12:15]
	v_mfma_f32_16x16x32_bf16 v[8:11], v[98:101], v[190:193], v[8:11]
	s_setprio 0
	s_barrier
; #define PG8_STAGE(bufoff, gbase, voff) do { _Pragma("unroll") for (int _i = 0; _i < 2; ++_i) \
;     __builtin_amdgcn_global_load_lds((const unsigned*)((const char*)(gbase) + (voff)[_i]), (LAS unsigned*)(lds + (bufoff) + ldsw + _i * 8192), 16, 0, 0); } while (0)
; #define PG8_LDA(dst, b, h) do { _Pragma("unroll") for (int m = 0; m < 4; ++m) _Pragma("unroll") for (int k = 0; k < 2; ++k) dst[m][k] = *(const LAS bf16x8*)(lds + PG8_SA(b, h) + aoff + m * 2048 + k * 1024); } while (0)
; #define PG8_LDB(dst, b, h) do { _Pragma("unroll") for (int n = 0; n < 2; ++n) _Pragma("unroll") for (int k = 0; k < 2; ++k) dst[n][k] = *(const LAS bf16x8*)(lds + PG8_SB(b, h) + boff + n * 2048 + k * 1024); } while (0)
; #define PG8_MMA(ai, bj, At, Bt) do { __builtin_amdgcn_s_setprio(1); _Pragma("unroll") for (int m = 0; m < 4; ++m) _Pragma("unroll") for (int n = 0; n < 2; ++n) _Pragma("unroll") for (int k = 0; k < 2; ++k) \
;     acc[ai][bj][m][n] = __builtin_amdgcn_mfma_f32_16x16x32_bf16(Bt[n][k], At[m][k], acc[ai][bj][m][n], 0, 0, 0); __builtin_amdgcn_s_setprio(0); } while (0)
; #define PG8_WAIT_V(n) asm volatile("s_waitcnt vmcnt(" #n ")" ::: "memory")
; #define PG8_WAIT_L(n) asm volatile("s_waitcnt lgkmcnt(" #n ")" ::: "memory")
; #define PG8_BAR __builtin_amdgcn_s_barrier()
; #define PG8_SCHED __builtin_amdgcn_sched_barrier(0)
; template <class Epi>
; __device__ __forceinline__ void gemm_phase(LAS unsigned char* lds, const Gemm g, const StaticOrder& S, const Epi& E, int wv0) {
;     ...
;       PG8_STAGE(PG8_SB(0, 1), b2 + hstepB, voffB);
;       PG8_WAIT_V(6); PG8_BAR; PG8_MMA(1, 1, At, B1); PG8_BAR;
;       PG8_LDB(B0, 1, 0); PG8_SCHED; PG8_LDA(At, 1, 0); PG8_STAGE(PG8_SA(0, 1), a2 + hstepA, voffA);
;       PG8_WAIT_L(8); PG8_BAR; PG8_WAIT_L(0); PG8_MMA(0, 0, At, B0); PG8_BAR; PG8_SCHED;
;       PG8_LDB(B1, 1, 1); PG8_STAGE(PG8_SB(1, 0), b3, voffB);
;       PG8_BAR; PG8_WAIT_L(0); PG8_MMA(0, 1, At, B1); PG8_BAR;
	s_add_u32 s18, s20, 0x20000
	s_addc_u32 s19, s21, 0
	s_add_i32 s0, s47, s31
	v_lshl_add_u64 v[72:73], s[18:19], 0, v[224:225]
	s_mov_b32 m0, s0
	s_nop 0
	global_load_lds_dwordx4 v[72:73], off
	v_lshl_add_u64 v[72:73], s[18:19], 0, v[228:229]
	s_add_i32 m0, s0, 0x2000
	s_nop 0
	global_load_lds_dwordx4 v[72:73], off
	s_waitcnt vmcnt(6)
	s_barrier
	s_setprio 1
	v_mfma_f32_16x16x32_bf16 v[52:55], v[178:181], v[122:125], v[52:55]
	v_mfma_f32_16x16x32_bf16 v[48:51], v[186:189], v[122:125], v[48:51]
	v_mfma_f32_16x16x32_bf16 v[36:39], v[178:181], v[140:143], v[36:39]
	v_mfma_f32_16x16x32_bf16 v[32:35], v[186:189], v[140:143], v[32:35]
	v_mfma_f32_16x16x32_bf16 v[20:23], v[178:181], v[148:151], v[20:23]
	v_mfma_f32_16x16x32_bf16 v[16:19], v[186:189], v[148:151], v[16:19]
	v_mfma_f32_16x16x32_bf16 v[4:7], v[178:181], v[164:167], v[4:7]
	v_mfma_f32_16x16x32_bf16 v[0:3], v[186:189], v[164:167], v[0:3]
	v_mfma_f32_16x16x32_bf16 v[52:55], v[182:185], v[136:139], v[52:55]
	v_mfma_f32_16x16x32_bf16 v[48:51], v[198:201], v[136:139], v[48:51]
	v_mfma_f32_16x16x32_bf16 v[36:39], v[182:185], v[144:147], v[36:39]
	v_mfma_f32_16x16x32_bf16 v[32:35], v[198:201], v[144:147], v[32:35]
	v_mfma_f32_16x16x32_bf16 v[20:23], v[182:185], v[160:163], v[20:23]
	v_mfma_f32_16x16x32_bf16 v[16:19], v[198:201], v[160:163], v[16:19]
	v_mfma_f32_16x16x32_bf16 v[4:7], v[182:185], v[190:193], v[4:7]
	v_mfma_f32_16x16x32_bf16 v[0:3], v[198:201], v[190:193], v[0:3]
	s_setprio 0
	s_add_i32 s0, 0, 0x18000
	v_add_u32_e32 v84, s0, v253
	s_barrier
	ds_read_b128 v[72:75], v84
	ds_read_b128 v[76:79], v84 offset:1024
	ds_read_b128 v[90:93], v84 offset:2048
	ds_read_b128 v[98:101], v84 offset:3072
	s_add_u32 s18, s22, 0x114000
	s_addc_u32 s19, s23, 0
	s_mov_b32 m0, s36
	v_lshl_add_u64 v[84:85], s[18:19], 0, v[94:95]
	ds_read_b128 v[122:125], v244 offset:32768
	ds_read_b128 v[136:139], v244 offset:33792
	ds_read_b128 v[140:143], v244 offset:34816
	ds_read_b128 v[144:147], v244 offset:35840
	ds_read_b128 v[148:151], v244 offset:36864
	ds_read_b128 v[178:181], v244 offset:37888
	ds_read_b128 v[206:209], v244 offset:38912
	ds_read_b128 v[210:213], v244 offset:39936
	global_load_lds_dwordx4 v[84:85], off
	v_lshl_add_u64 v[84:85], s[18:19], 0, v[226:227]
	s_mov_b32 m0, s37
	s_nop 0
	global_load_lds_dwordx4 v[84:85], off
	s_waitcnt lgkmcnt(8)
	s_barrier
	s_waitcnt lgkmcnt(0)
	s_setprio 1
	s_waitcnt lgkmcnt(0)
	v_mfma_f32_16x16x32_bf16 v[152:155], v[72:75], v[122:125], v[152:155]
	v_mfma_f32_16x16x32_bf16 v[202:205], v[76:79], v[136:139], v[152:155]
	v_mfma_f32_16x16x32_bf16 v[152:155], v[90:93], v[122:125], v[156:159]
	v_mfma_f32_16x16x32_bf16 v[198:201], v[98:101], v[136:139], v[152:155]
	v_mfma_f32_16x16x32_bf16 v[152:155], v[72:75], v[140:143], v[170:173]
	v_mfma_f32_16x16x32_bf16 v[186:189], v[76:79], v[144:147], v[152:155]
	v_mfma_f32_16x16x32_bf16 v[152:155], v[90:93], v[140:143], v[174:177]
	v_mfma_f32_16x16x32_bf16 v[130:133], v[72:75], v[148:151], v[132:135]
	v_mfma_f32_16x16x32_bf16 v[126:129], v[90:93], v[148:151], v[126:129]
	v_mfma_f32_16x16x32_bf16 v[84:87], v[72:75], v[206:209], v[86:89]
	v_mfma_f32_16x16x32_bf16 v[80:83], v[90:93], v[206:209], v[80:83]
	v_mfma_f32_16x16x32_bf16 v[182:185], v[98:101], v[144:147], v[152:155]
	v_mfma_f32_16x16x32_bf16 v[132:135], v[76:79], v[178:181], v[130:133]
	v_mfma_f32_16x16x32_bf16 v[128:131], v[98:101], v[178:181], v[126:129]
	v_mfma_f32_16x16x32_bf16 v[86:89], v[76:79], v[210:213], v[84:87]
	v_mfma_f32_16x16x32_bf16 v[82:85], v[98:101], v[210:213], v[80:83]
	s_setprio 0
	s_barrier
	s_add_i32 s22, 0, 0x1c000
	v_add_u32_e32 v80, s22, v253
	s_add_i32 s0, s0, s31
	ds_read_b128 v[152:155], v80
	ds_read_b128 v[156:159], v80 offset:1024
	ds_read_b128 v[170:173], v80 offset:2048
	ds_read_b128 v[174:177], v80 offset:3072
	v_lshl_add_u64 v[80:81], v[214:215], 0, s[72:73]
	s_mov_b32 m0, s0
	s_nop 0
	global_load_lds_dwordx4 v[80:81], off
	v_lshl_add_u64 v[80:81], v[216:217], 0, s[72:73]
	s_add_i32 m0, s0, 0x2000
	s_nop 0
	global_load_lds_dwordx4 v[80:81], off
	s_barrier
	s_waitcnt lgkmcnt(0)
	s_setprio 1
	s_waitcnt lgkmcnt(0)
	v_mfma_f32_16x16x32_bf16 v[110:113], v[170:173], v[122:125], v[110:113]
	v_mfma_f32_16x16x32_bf16 v[190:193], v[174:177], v[136:139], v[110:113]
	v_mfma_f32_16x16x32_bf16 v[110:113], v[152:155], v[140:143], v[114:117]
	v_mfma_f32_16x16x32_bf16 v[160:163], v[152:155], v[122:125], v[194:197]
	v_mfma_f32_16x16x32_bf16 v[166:169], v[156:159], v[144:147], v[110:113]
	v_mfma_f32_16x16x32_bf16 v[110:113], v[170:173], v[140:143], v[118:121]
	v_mfma_f32_16x16x32_bf16 v[106:109], v[152:155], v[148:151], v[106:109]
	v_mfma_f32_16x16x32_bf16 v[102:105], v[170:173], v[148:151], v[102:105]
	v_mfma_f32_16x16x32_bf16 v[68:71], v[152:155], v[206:209], v[68:71]
	v_mfma_f32_16x16x32_bf16 v[64:67], v[170:173], v[206:209], v[64:67]
	v_mfma_f32_16x16x32_bf16 v[194:197], v[156:159], v[136:139], v[160:163]
	v_mfma_f32_16x16x32_bf16 v[162:165], v[174:177], v[144:147], v[110:113]
	v_mfma_f32_16x16x32_bf16 v[106:109], v[156:159], v[178:181], v[106:109]
	v_mfma_f32_16x16x32_bf16 v[102:105], v[174:177], v[178:181], v[102:105]
	v_mfma_f32_16x16x32_bf16 v[68:71], v[156:159], v[210:213], v[68:71]
	v_mfma_f32_16x16x32_bf16 v[64:67], v[174:177], v[210:213], v[64:67]
	s_setprio 0
	s_mov_b32 m0, s38
	v_lshl_add_u64 v[80:81], v[218:219], 0, s[72:73]
	s_barrier
; #define PG8_STAGE(bufoff, gbase, voff) do { _Pragma("unroll") for (int _i = 0; _i < 2; ++_i) \
;     __builtin_amdgcn_global_load_lds((const unsigned*)((const char*)(gbase) + (voff)[_i]), (LAS unsigned*)(lds + (bufoff) + ldsw + _i * 8192), 16, 0, 0); } while (0)
; #define PG8_LDA(dst, b, h) do { _Pragma("unroll") for (int m = 0; m < 4; ++m) _Pragma("unroll") for (int k = 0; k < 2; ++k) dst[m][k] = *(const LAS bf16x8*)(lds + PG8_SA(b, h) + aoff + m * 2048 + k * 1024); } while (0)
; #define PG8_MMA(ai, bj, At, Bt) do { __builtin_amdgcn_s_setprio(1); _Pragma("unroll") for (int m = 0; m < 4; ++m) _Pragma("unroll") for (int n = 0; n < 2; ++n) _Pragma("unroll") for (int k = 0; k < 2; ++k) \
;     acc[ai][bj][m][n] = __builtin_amdgcn_mfma_f32_16x16x32_bf16(Bt[n][k], At[m][k], acc[ai][bj][m][n], 0, 0, 0); __builtin_amdgcn_s_setprio(0); } while (0)
; #define PG8_WAIT_V(n) asm volatile("s_waitcnt vmcnt(" #n ")" ::: "memory")
; #define PG8_WAIT_L(n) asm volatile("s_waitcnt lgkmcnt(" #n ")" ::: "memory")
; #define PG8_BAR __builtin_amdgcn_s_barrier()
; #define PG8_SCHED __builtin_amdgcn_sched_barrier(0)
; template <class Epi>
; __device__ __forceinline__ void gemm_phase(LAS unsigned char* lds, const Gemm g, const StaticOrder& S, const Epi& E, int wv0) {
;     ...
;       PG8_LDA(At, 1, 1); PG8_STAGE(PG8_SA(1, 0), a3, voffA);
;       PG8_BAR; PG8_WAIT_L(0); PG8_MMA(1, 0, At, B0); PG8_BAR; PG8_SCHED;
;       PG8_STAGE(PG8_SB(1, 1), b3 + hstepB, voffB);
;       PG8_WAIT_V(6); PG8_BAR; PG8_MMA(1, 1, At, B1); PG8_BAR;
;     }
;     E(acc, cur, wr, wc, fr, fq);
;   __device__ __forceinline__ void operator()(const f32x4 (&acc)[2][2][4][2], const pg8::Unit& u, int wr, int wc, int fr, int fq) const {
;     ...
;       for (int m = 0; m < 4; ++m) { hs[ai][m] = 0.f;
;         if (MODE == E_UQ) hs[ai][m] = ((const f32x4*)e.f0)[row0 + ai * 128 + m * 16].x * MLA_QSCALE;
;         if (MODE == E_UKV) hs[ai][m] = ((const f32x4*)e.f0)[row0 + ai * 128 + m * 16].y; }
;     EpiPre q[2][4];
; #pragma unroll
;     for (int i = 0; i < 4; ++i) preload(q[0][i], row0 + (i >> 1) * 16, col0 + (i & 1) * 128);
	ds_read_b128 v[110:113], v244 offset:49152
	ds_read_b128 v[114:117], v244 offset:50176
	ds_read_b128 v[118:121], v244 offset:51200
	ds_read_b128 v[122:125], v244 offset:52224
	ds_read_b128 v[136:139], v244 offset:53248
	ds_read_b128 v[140:143], v244 offset:54272
	ds_read_b128 v[144:147], v244 offset:55296
	ds_read_b128 v[148:151], v244 offset:56320
	global_load_lds_dwordx4 v[80:81], off
	v_lshl_add_u64 v[80:81], v[220:221], 0, s[72:73]
	s_mov_b32 m0, s39
	s_nop 0
	global_load_lds_dwordx4 v[80:81], off
	s_barrier
	s_waitcnt lgkmcnt(0)
	s_setprio 1
	s_waitcnt lgkmcnt(0)
	v_mfma_f32_16x16x32_bf16 v[60:63], v[72:75], v[110:113], v[60:63]
	v_mfma_f32_16x16x32_bf16 v[56:59], v[90:93], v[110:113], v[56:59]
	v_mfma_f32_16x16x32_bf16 v[44:47], v[72:75], v[118:121], v[44:47]
	v_mfma_f32_16x16x32_bf16 v[40:43], v[90:93], v[118:121], v[40:43]
	v_mfma_f32_16x16x32_bf16 v[28:31], v[72:75], v[136:139], v[28:31]
	v_mfma_f32_16x16x32_bf16 v[24:27], v[90:93], v[136:139], v[24:27]
	v_mfma_f32_16x16x32_bf16 v[12:15], v[72:75], v[144:147], v[12:15]
	v_mfma_f32_16x16x32_bf16 v[8:11], v[90:93], v[144:147], v[8:11]
	v_mfma_f32_16x16x32_bf16 v[60:63], v[76:79], v[114:117], v[60:63]
	v_mfma_f32_16x16x32_bf16 v[56:59], v[98:101], v[114:117], v[56:59]
	v_mfma_f32_16x16x32_bf16 v[44:47], v[76:79], v[122:125], v[44:47]
	v_mfma_f32_16x16x32_bf16 v[40:43], v[98:101], v[122:125], v[40:43]
	v_mfma_f32_16x16x32_bf16 v[28:31], v[76:79], v[140:143], v[28:31]
	v_mfma_f32_16x16x32_bf16 v[24:27], v[98:101], v[140:143], v[24:27]
	v_mfma_f32_16x16x32_bf16 v[12:15], v[76:79], v[148:151], v[12:15]
	v_mfma_f32_16x16x32_bf16 v[8:11], v[98:101], v[148:151], v[8:11]
	s_setprio 0
	s_barrier
	s_add_u32 s18, s20, 0x20080
	s_addc_u32 s19, s21, 0
	s_add_i32 s0, s22, s31
	v_lshl_add_u64 v[72:73], s[18:19], 0, v[224:225]
	s_mov_b32 m0, s0
	s_nop 0
	global_load_lds_dwordx4 v[72:73], off
	v_lshl_add_u64 v[72:73], s[18:19], 0, v[228:229]
	s_add_i32 m0, s0, 0x2000
	s_nop 0
	global_load_lds_dwordx4 v[72:73], off
	s_waitcnt vmcnt(6)
	s_barrier
	s_setprio 1
	v_mfma_f32_16x16x32_bf16 v[52:55], v[152:155], v[110:113], v[52:55]
	v_mfma_f32_16x16x32_bf16 v[48:51], v[170:173], v[110:113], v[48:51]
	v_mfma_f32_16x16x32_bf16 v[36:39], v[152:155], v[118:121], v[36:39]
	v_mfma_f32_16x16x32_bf16 v[32:35], v[170:173], v[118:121], v[32:35]
	v_mfma_f32_16x16x32_bf16 v[20:23], v[152:155], v[136:139], v[20:23]
	v_mfma_f32_16x16x32_bf16 v[16:19], v[170:173], v[136:139], v[16:19]
	v_mfma_f32_16x16x32_bf16 v[4:7], v[152:155], v[144:147], v[4:7]
	v_mfma_f32_16x16x32_bf16 v[0:3], v[170:173], v[144:147], v[0:3]
	v_mfma_f32_16x16x32_bf16 v[52:55], v[156:159], v[114:117], v[52:55]
	v_mfma_f32_16x16x32_bf16 v[48:51], v[174:177], v[114:117], v[48:51]
	v_mfma_f32_16x16x32_bf16 v[36:39], v[156:159], v[122:125], v[36:39]
	v_mfma_f32_16x16x32_bf16 v[32:35], v[174:177], v[122:125], v[32:35]
	v_mfma_f32_16x16x32_bf16 v[20:23], v[156:159], v[140:143], v[20:23]
	v_mfma_f32_16x16x32_bf16 v[16:19], v[174:177], v[140:143], v[16:19]
	v_mfma_f32_16x16x32_bf16 v[4:7], v[156:159], v[148:151], v[4:7]
	v_mfma_f32_16x16x32_bf16 v[0:3], v[174:177], v[148:151], v[0:3]
	s_setprio 0
	s_add_i32 s46, s46, 2
	s_add_u32 s44, s44, 0x100
	s_addc_u32 s45, s45, 0
	s_cmp_gt_u32 s46, 5
	s_mov_b64 s[18:19], s[4:5]
	s_barrier
	s_cbranch_scc0 .LBB0_671
	v_lshl_add_u32 v234, s1, 8, v252
	v_or_b32_e32 v238, 32, v234
	v_ashrrev_i32_e32 v239, 31, v238
	v_or_b32_e32 v236, 48, v234
	v_ashrrev_i32_e32 v235, 31, v234
	v_lshl_add_u64 v[76:77], v[238:239], 4, s[68:69]
	v_ashrrev_i32_e32 v237, 31, v236
	v_lshl_add_u64 v[72:73], v[234:235], 4, s[68:69]
	v_lshl_add_u64 v[78:79], v[236:237], 4, s[68:69]
	global_load_dwordx4 v[210:213], v[76:77], off
	global_load_dwordx4 v[206:209], v[78:79], off
	global_load_dwordx4 v[216:219], v[72:73], off
	global_load_dwordx4 v[178:181], v[72:73], off offset:2048
	global_load_dwordx4 v[144:147], v[72:73], off offset:2304
	global_load_dwordx4 v[110:113], v[72:73], off offset:2560
	v_or_b32_e32 v240, 16, v234
	v_ashrrev_i32_e32 v241, 31, v240
	v_lshl_add_u64 v[74:75], v[240:241], 4, s[68:69]
	global_load_dwordx4 v[212:215], v[74:75], off
	s_nop 0
	global_load_dwordx4 v[72:75], v[72:73], off offset:2816
	s_waitcnt vmcnt(0)
	v_lshl_or_b32 v180, s16, 8, v254
	v_mul_hi_i32 v73, v180, s71
	v_lshrrev_b32_e32 v74, 31, v73
	v_lshrrev_b32_e32 v73, 5, v73
	v_add_u32_e32 v73, v73, v74
	v_mul_lo_u32 v73, v73, s59
	v_sub_u32_e32 v96, v180, v73
	v_lshlrev_b64 v[74:75], 8, v[234:235]
	v_cmp_lt_i32_e64 s[4:5], s67, v96
	v_lshl_add_u64 v[74:75], s[8:9], 0, v[74:75]
	s_and_saveexec_b64 s[16:17], s[4:5]
	s_cbranch_execz .LBB0_674
	v_lshl_add_u64 v[76:77], v[96:97], 2, v[74:75]
	global_load_dwordx4 v[170:173], v[76:77], off offset:-496
	global_load_dwordx4 v[174:177], v[76:77], off offset:-512

; __device__ __forceinline__ int otid(int wv0) { int t = (wv0 << 6) | olane(); asm volatile("" : "+v"(t)); return t; }
; __device__ __forceinline__ int obid() { int b = blockIdx.x; asm volatile("" : "+s"(b)); return b; }
; __device__ __forceinline__ int ogrid() { int g = gridDim.x; asm volatile("" : "+s"(g)); return g; }
; __device__ __forceinline__ void mla_phase(KP p, LAS unsigned char* lds, int wv0) {
;     ...
;   const int tid = otid(wv0), wid = __builtin_amdgcn_readfirstlane(tid >> 6), lane = tid & 63, c = lane & 31, hh = lane >> 5;
;   const int G = ogrid(), bid = obid();
;   for (int k = 0; k * G < 1024; ++k) {
;     const int idx = (k & 1) ? (G - 1 - bid) : bid, rank = k * G + idx;
;     if (rank >= 1024) continue;
;     const int qb = 15 - rank / 64, bh = rank % 64, b = bh >> 4, hd = bh & 15;
;     const int tok0 = b * SEQ, q0 = qb * 256 + 32 * wid;
;     bf16x8 qf[12];
;     { const bf16_t* qrow = q + (size_t)(tok0 + q0 + c) * NQ + hd * 192 + 8 * hh;
; #pragma unroll
;       for (int st = 0; st < 12; ++st) qf[st] = *(const bf16x8*)(qrow + 16 * st); }
;     f32x16 o[4];
; #pragma unroll
;     for (int d = 0; d < 4; ++d)
; #pragma unroll
;       for (int r = 0; r < 16; ++r) o[d][r] = 0.f;
;     float m = -1e30f, l = 0.f;
;     const int ntiles = qb * 4 + 4;
;     unsigned ksrc[3]; int kdst[3];
;     const unsigned char* wsb = p->ws;
; #pragma unroll
;     for (int i = 0; i < 3; ++i) { const int cid = tid + 512 * i, key = cid / 24, ch = cid % 24;
;       ksrc[i] = (ch < 16) ? (unsigned)(O_KV + ((size_t)(tok0 + key) * NKV + hd * 256 + ch * 8) * 2) : (unsigned)(O_H + ((size_t)(tok0 + key) * LDH + C_KR + (ch - 16) * 8) * 2);
;       kdst[i] = key * KSTR + ch * 16; }
;     const unsigned kinc0 = 64u * NKV * 2u, kinc1 = 64u * LDH * 2u;
;     const bool k2rope = ((tid + 1024) % 24) >= 16, k1rope = ((tid + 512) % 24) >= 16, k0rope = (tid % 24) >= 16;
;     unsigned vsrc[2]; int vdst[2];
; #pragma unroll
;     for (int i = 0; i < 2; ++i) { const int cid = tid + 512 * i, key = cid >> 4, ch = cid & 15;
;       vsrc[i] = (unsigned)(O_KV + ((size_t)(tok0 + key) * NKV + hd * 256 + 128 + ch * 8) * 2); vdst[i] = key * VSTR + ch * 16; }
.LBB0_820:
	s_or_b64 exec, exec, s[2:3]
	s_mov_b32 s66, s48
	s_waitcnt lgkmcnt(0)
	s_barrier
	s_load_dwordx2 s[12:13], s[54:55], 0xd0
	s_mov_b32 s1, -1
	s_mov_b32 s17, s60
	v_mbcnt_lo_u32_b32 v0, s1, 0
	s_waitcnt lgkmcnt(0)
	s_add_u32 s14, s12, 0x19300000
	s_addc_u32 s15, s13, 0
	s_lshl_b32 s16, s53, 6
	v_mbcnt_hi_u32_b32 v0, s1, v0
	v_or_b32_e32 v1, s16, v0
	s_mov_b32 s18, s82
	v_add_u32_e32 v3, 0x400, v1
	v_mul_hi_i32 v4, v3, s71
	v_lshrrev_b32_e32 v5, 31, v4
	v_ashrrev_i32_e32 v4, 2, v4
	v_add_u32_e32 v183, v4, v5
	v_mul_lo_u32 v4, v183, 24
	v_sub_u32_e32 v3, v3, v4
	v_add_u32_e32 v4, 0x200, v1
	v_mul_hi_i32 v5, v4, s71
	v_lshrrev_b32_e32 v6, 31, v5
	v_ashrrev_i32_e32 v5, 2, v5
	v_add_u32_e32 v185, v5, v6
	v_mul_hi_i32 v6, v1, s71
	v_lshrrev_b32_e32 v7, 31, v6
	v_ashrrev_i32_e32 v6, 2, v6
	v_add_u32_e32 v187, v6, v7
	v_mul_lo_u32 v5, v185, 24
	v_mul_lo_u32 v6, v187, 24
	s_not_b32 s2, s18
	v_sub_u32_e32 v5, v4, v5
	v_sub_u32_e32 v6, v1, v6
	v_lshlrev_b32_e32 v7, 4, v1
	v_bfe_u32 v2, v1, 5, 1
	s_add_i32 s19, s17, s2
	v_and_b32_e32 v196, 0xf0, v7
	v_cmp_lt_i32_e64 s[2:3], 15, v6
	v_mov_b32_e32 v7, 0x80000
	v_mov_b32_e32 v8, 0x8a000
	v_cmp_lt_i32_e64 s[4:5], 15, v5
	v_cmp_lt_i32_e64 s[6:7], 15, v3
	v_cndmask_b32_e64 v197, v7, v8, s[2:3]
	v_cndmask_b32_e64 v198, v7, v8, s[4:5]
	v_cndmask_b32_e64 v199, v7, v8, s[6:7]
	v_lshlrev_b32_e32 v180, 2, v2
	v_lshrrev_b32_e32 v7, 2, v1
	v_readfirstlane_b32 s1, v1
	v_and_or_b32 v7, v7, 3, v180
	s_ashr_i32 s20, s1, 1
	v_lshlrev_b32_e32 v0, 3, v2
	v_lshlrev_b32_e32 v201, 4, v2
	v_and_b32_e32 v2, 16, v1
	v_mul_u32_u24_e32 v202, 0x140, v7
	v_lshlrev_b32_e32 v7, 2, v1
	s_movk_i32 s1, 0x190
	v_and_b32_e32 v181, 31, v1
	v_and_or_b32 v2, v7, 12, v2
	v_lshlrev_b32_e32 v204, 4, v6
	v_mul_lo_u32 v205, v187, s1
	v_lshlrev_b32_e32 v206, 4, v5
	v_mul_lo_u32 v207, v185, s1
	v_lshlrev_b32_e32 v208, 4, v3
	v_mul_lo_u32 v209, v183, s1
	v_ashrrev_i32_e32 v210, 4, v1
	s_movk_i32 s1, 0x140
	v_ashrrev_i32_e32 v212, 4, v4
	s_mov_b32 s0, 0
	s_andn2_b32 s20, s20, 31
	v_mul_u32_u24_e32 v200, 0x190, v181
	v_lshlrev_b32_e32 v203, 1, v2
	v_add_u32_e32 v182, 0x10900900, v204
	v_add_u32_e32 v184, 0x10900900, v206
	v_add_u32_e32 v186, 0x10900900, v208
	v_mul_lo_u32 v211, v210, s1
	v_mul_lo_u32 v213, v212, s1
	v_or_b32_e32 v214, 0x1f300100, v196
	v_lshlrev_b32_e32 v188, 1, v0
	s_mov_b32 s21, 0
	v_lshl_add_u32 v0, v180, 3, v181
	s_lshl_b32 s63, s53, 6
	s_mov_b32 s64, 0x51eb851f
	s_mov_b32 s65, 0xcccccccd
	s_mov_b32 s37, 0x10900900
	s_add_u32 s47, s63, 0
	v_add_u32_e32 v1, s47, v0
	v_mul_hi_u32 v2, v1, s64
	v_lshrrev_b32_e32 v2, 3, v2
	v_mul_u32_u24_e32 v3, 25, v2
	v_sub_u32_e32 v3, v1, v3
	v_min_u32_e32 v3, 23, v3
	v_lshlrev_b32_e32 v4, 4, v3
	v_lshl_add_u32 v5, v2, 13, v4
	v_add_u32_e32 v5, 0x1f300000, v5
	v_mul_u32_u24_e32 v6, 0x2280, v2
	v_add3_u32 v6, v6, v4, s37
	v_cmp_gt_u32_e32 vcc, 16, v3
	v_mov_b32_e32 v7, 0x8a000
	v_mov_b32_e32 v8, 0x80000
	v_cndmask_b32_e32 v204, v6, v5, vcc
	v_cndmask_b32_e32 v210, v7, v8, vcc
	s_lshl_b32 s48, s47, 4
	s_add_u32 s47, s63, 512
	v_add_u32_e32 v1, s47, v0
	v_mul_hi_u32 v2, v1, s64
	v_lshrrev_b32_e32 v2, 3, v2
	v_mul_u32_u24_e32 v3, 25, v2
	v_sub_u32_e32 v3, v1, v3
	v_min_u32_e32 v3, 23, v3
	v_lshlrev_b32_e32 v4, 4, v3
	v_lshl_add_u32 v5, v2, 13, v4
	v_add_u32_e32 v5, 0x1f300000, v5
	v_mul_u32_u24_e32 v6, 0x2280, v2
	v_add3_u32 v6, v6, v4, s37
	v_cmp_gt_u32_e32 vcc, 16, v3
	v_mov_b32_e32 v7, 0x8a000
	v_mov_b32_e32 v8, 0x80000
	v_cndmask_b32_e32 v205, v6, v5, vcc
	v_cndmask_b32_e32 v211, v7, v8, vcc
	s_lshl_b32 s49, s47, 4
	s_add_u32 s47, s63, 1024
	v_add_u32_e32 v1, s47, v0
	v_mul_hi_u32 v2, v1, s64
	v_lshrrev_b32_e32 v2, 3, v2
	v_mul_u32_u24_e32 v3, 25, v2
	v_sub_u32_e32 v3, v1, v3
	v_min_u32_e32 v3, 23, v3
	v_lshlrev_b32_e32 v4, 4, v3
	v_lshl_add_u32 v5, v2, 13, v4
	v_add_u32_e32 v5, 0x1f300000, v5
	v_mul_u32_u24_e32 v6, 0x2280, v2
	v_add3_u32 v6, v6, v4, s37
	v_cmp_gt_u32_e32 vcc, 16, v3
	v_mov_b32_e32 v7, 0x8a000
	v_mov_b32_e32 v8, 0x80000
	v_cndmask_b32_e32 v206, v6, v5, vcc
	v_cndmask_b32_e32 v212, v7, v8, vcc
	s_lshl_b32 s50, s47, 4
	s_add_u32 s47, s63, 0
	v_add_u32_e32 v1, s47, v0
	v_mul_hi_u32 v2, v1, s65
	v_lshrrev_b32_e32 v2, 4, v2
	v_mul_u32_u24_e32 v3, 20, v2
	v_sub_u32_e32 v3, v1, v3
	v_min_u32_e32 v3, 15, v3
	v_lshlrev_b32_e32 v4, 4, v3
	v_lshl_add_u32 v5, v2, 13, v4
	v_add_u32_e32 v207, 0x1f300100, v5
	v_mov_b32_e32 v213, 0x80000
	s_lshl_b32 s51, s47, 4
	s_add_u32 s47, s63, 512
	v_add_u32_e32 v1, s47, v0
	v_mul_hi_u32 v2, v1, s65
	v_lshrrev_b32_e32 v2, 4, v2
	v_mul_u32_u24_e32 v3, 20, v2
	v_sub_u32_e32 v3, v1, v3
	v_min_u32_e32 v3, 15, v3
	v_lshlrev_b32_e32 v4, 4, v3
	v_lshl_add_u32 v5, v2, 13, v4
	v_add_u32_e32 v208, 0x1f300100, v5
	v_mov_b32_e32 v196, 0x80000
	s_lshl_b32 s52, s47, 4
	s_cmp_eq_u32 s53, 0
	s_cbranch_scc0 .Lmlapre_not0
	s_movk_i32 s47, 0x600
	v_add_u32_e32 v1, s47, v0
	v_mul_hi_u32 v2, v1, s64
	v_lshrrev_b32_e32 v2, 3, v2
	v_mul_u32_u24_e32 v3, 25, v2
	v_sub_u32_e32 v3, v1, v3
	v_min_u32_e32 v3, 23, v3
	v_lshlrev_b32_e32 v4, 4, v3
	v_lshl_add_u32 v5, v2, 13, v4
	v_add_u32_e32 v5, 0x1f300000, v5
	v_mul_u32_u24_e32 v6, 0x2280, v2
	v_add3_u32 v6, v6, v4, s37
	v_cmp_gt_u32_e32 vcc, 16, v3
	v_mov_b32_e32 v7, 0x8a000
	v_mov_b32_e32 v8, 0x80000
	v_cndmask_b32_e32 v209, v6, v5, vcc
	v_cndmask_b32_e32 v197, v7, v8, vcc
	s_movk_i32 s56, 0x6000
	s_mov_b32 s58, 1
	s_branch .Lmlapre_done
; __device__ __forceinline__ float frcp(float x) { return __builtin_amdgcn_rcpf(x); }
; __device__ __forceinline__ void mla_phase(KP p, LAS unsigned char* lds, int wv0) {
;     ...
;     unsigned ksrc[3]; int kdst[3];
;     const unsigned char* wsb = p->ws;
; #pragma unroll
;     for (int i = 0; i < 3; ++i) { const int cid = tid + 512 * i, key = cid / 24, ch = cid % 24;
;       ksrc[i] = (ch < 16) ? (unsigned)(O_KV + ((size_t)(tok0 + key) * NKV + hd * 256 + ch * 8) * 2) : (unsigned)(O_H + ((size_t)(tok0 + key) * LDH + C_KR + (ch - 16) * 8) * 2);
;       kdst[i] = key * KSTR + ch * 16; }
;     const unsigned kinc0 = 64u * NKV * 2u, kinc1 = 64u * LDH * 2u;
;     const bool k2rope = ((tid + 1024) % 24) >= 16, k1rope = ((tid + 512) % 24) >= 16, k0rope = (tid % 24) >= 16;
;     unsigned vsrc[2]; int vdst[2];
; #pragma unroll
;     for (int i = 0; i < 2; ++i) { const int cid = tid + 512 * i, key = cid >> 4, ch = cid & 15;
;       vsrc[i] = (unsigned)(O_KV + ((size_t)(tok0 + key) * NKV + hd * 256 + 128 + ch * 8) * 2); vdst[i] = key * VSTR + ch * 16; }
;     ...
;     const float inv = frcp(l + __shfl_xor(l, 32));
;     bf16_t* yrow = h + (size_t)(tok0 + q0 + c) * LDH + C_CQ + hd * 128 + 4 * hh;
; #pragma unroll
;     for (int d = 0; d < 4; ++d)
; #pragma unroll
;       for (int g = 0; g < 4; ++g) { u32x2 w; w.x = pk2(o[d][4 * g] * inv, o[d][4 * g + 1] * inv); w.y = pk2(o[d][4 * g + 2] * inv, o[d][4 * g + 3] * inv);
;         *(u32x2*)(yrow + 32 * d + 8 * g) = w; }
.Lmlapre_not0:
	s_add_u32 s47, s53, 15
	s_lshl_b32 s47, s47, 6
	v_add_u32_e32 v1, s47, v0
	v_mul_hi_u32 v2, v1, s65
	v_lshrrev_b32_e32 v2, 4, v2
	v_mul_u32_u24_e32 v3, 20, v2
	v_sub_u32_e32 v3, v1, v3
	v_min_u32_e32 v3, 15, v3
	v_lshlrev_b32_e32 v4, 4, v3
	v_lshl_add_u32 v5, v2, 13, v4
	v_add_u32_e32 v209, 0x1f300100, v5
	v_mov_b32_e32 v197, 0x80000
	s_lshl_b32 s56, s47, 4
	s_mov_b32 s58, 2
	s_cmp_le_u32 s53, 4
	s_cselect_b32 s58, s58, 0
	s_cmp_le_u32 s53, 4
	s_cbranch_scc1 .Lmlapre_done
	v_mov_b32_e32 v209, v208
.Lmlapre_done:
	s_branch .LBB0_823
.LBB0_821:
	v_and_b32_e32 v65, 64, v251
	v_xor_b32_e32 v64, 32, v251
	v_add_u32_e32 v65, 64, v65
	v_cmp_lt_i32_e32 vcc, v64, v65
	s_lshl_b32 s92, s1, 8
	v_lshlrev_b32_e32 v96, 1, v180
	v_cndmask_b32_e32 v64, v251, v64, vcc
	v_lshlrev_b32_e32 v64, 2, v64
	ds_bpermute_b32 v66, v64, v216
	v_mov_b64_e32 v[64:65], s[12:13]
	v_mad_i64_i32 v[64:65], s[8:9], v215, s91, v[64:65]
	v_lshl_add_u64 v[64:65], v[64:65], 0, s[92:93]
	s_waitcnt lgkmcnt(0)
	v_add_f32_e32 v66, v216, v66
	v_rcp_f32_e32 v66, v66
	v_lshl_add_u64 v[64:65], v[64:65], 0, v[96:97]
	s_mov_b64 s[0:1], 0x10901280
	v_lshl_add_u64 v[68:69], v[64:65], 0, s[0:1]
	v_pk_mul_f32 v[48:49], v[48:49], v[66:67] op_sel_hi:[1,0]
	v_pk_mul_f32 v[50:51], v[50:51], v[66:67] op_sel_hi:[1,0]
	s_mov_b32 s0, 0x10901000
	v_cvt_pk_bf16_f32 v48, v48, v49
	v_cvt_pk_bf16_f32 v49, v50, v51
	v_add_co_u32_e32 v50, vcc, s0, v64
	v_pk_mul_f32 v[32:33], v[32:33], v[66:67] op_sel_hi:[1,0]
	v_pk_mul_f32 v[34:35], v[34:35], v[66:67] op_sel_hi:[1,0]
	v_pk_mul_f32 v[16:17], v[16:17], v[66:67] op_sel_hi:[1,0]
	v_pk_mul_f32 v[18:19], v[18:19], v[66:67] op_sel_hi:[1,0]
	v_pk_mul_f32 v[0:1], v[0:1], v[66:67] op_sel_hi:[1,0]
	v_pk_mul_f32 v[2:3], v[2:3], v[66:67] op_sel_hi:[1,0]
	v_addc_co_u32_e32 v51, vcc, 0, v65, vcc
	v_cvt_pk_bf16_f32 v32, v32, v33
	v_cvt_pk_bf16_f32 v33, v34, v35
	v_cvt_pk_bf16_f32 v16, v16, v17
	v_cvt_pk_bf16_f32 v17, v18, v19
	v_cvt_pk_bf16_f32 v0, v0, v1
	v_cvt_pk_bf16_f32 v1, v2, v3
	global_store_dwordx2 v[50:51], v[48:49], off offset:640
	v_pk_mul_f32 v[48:49], v[52:53], v[66:67] op_sel_hi:[1,0]
	v_pk_mul_f32 v[50:51], v[54:55], v[66:67] op_sel_hi:[1,0]
	global_store_dwordx2 v[68:69], v[32:33], off offset:64
	v_pk_mul_f32 v[32:33], v[36:37], v[66:67] op_sel_hi:[1,0]
	v_pk_mul_f32 v[34:35], v[38:39], v[66:67] op_sel_hi:[1,0]
	global_store_dwordx2 v[68:69], v[16:17], off offset:128
	v_pk_mul_f32 v[16:17], v[20:21], v[66:67] op_sel_hi:[1,0]
	v_pk_mul_f32 v[18:19], v[22:23], v[66:67] op_sel_hi:[1,0]
	global_store_dwordx2 v[68:69], v[0:1], off offset:192
	v_pk_mul_f32 v[0:1], v[4:5], v[66:67] op_sel_hi:[1,0]
	v_pk_mul_f32 v[2:3], v[6:7], v[66:67] op_sel_hi:[1,0]
	v_cvt_pk_bf16_f32 v48, v48, v49
	v_cvt_pk_bf16_f32 v49, v50, v51
	v_cvt_pk_bf16_f32 v32, v32, v33
	v_cvt_pk_bf16_f32 v33, v34, v35
	v_cvt_pk_bf16_f32 v16, v16, v17
	v_cvt_pk_bf16_f32 v17, v18, v19
	v_cvt_pk_bf16_f32 v0, v0, v1
	v_cvt_pk_bf16_f32 v1, v2, v3
	global_store_dwordx2 v[68:69], v[48:49], off offset:16
	v_pk_mul_f32 v[48:49], v[56:57], v[66:67] op_sel_hi:[1,0]
	v_pk_mul_f32 v[50:51], v[58:59], v[66:67] op_sel_hi:[1,0]
	global_store_dwordx2 v[68:69], v[32:33], off offset:80
	v_pk_mul_f32 v[32:33], v[40:41], v[66:67] op_sel_hi:[1,0]
	v_pk_mul_f32 v[34:35], v[42:43], v[66:67] op_sel_hi:[1,0]
	global_store_dwordx2 v[68:69], v[16:17], off offset:144
	v_pk_mul_f32 v[16:17], v[24:25], v[66:67] op_sel_hi:[1,0]
	v_pk_mul_f32 v[18:19], v[26:27], v[66:67] op_sel_hi:[1,0]
	global_store_dwordx2 v[68:69], v[0:1], off offset:208
	v_pk_mul_f32 v[0:1], v[8:9], v[66:67] op_sel_hi:[1,0]
	v_pk_mul_f32 v[2:3], v[10:11], v[66:67] op_sel_hi:[1,0]
	v_cvt_pk_bf16_f32 v48, v48, v49
	v_cvt_pk_bf16_f32 v49, v50, v51
	v_cvt_pk_bf16_f32 v32, v32, v33
	v_cvt_pk_bf16_f32 v33, v34, v35
	v_cvt_pk_bf16_f32 v16, v16, v17
	v_cvt_pk_bf16_f32 v17, v18, v19
	v_cvt_pk_bf16_f32 v0, v0, v1
	v_cvt_pk_bf16_f32 v1, v2, v3
	global_store_dwordx2 v[68:69], v[48:49], off offset:32
	v_pk_mul_f32 v[48:49], v[60:61], v[66:67] op_sel_hi:[1,0]
	v_pk_mul_f32 v[50:51], v[62:63], v[66:67] op_sel_hi:[1,0]
	global_store_dwordx2 v[68:69], v[32:33], off offset:96
	v_pk_mul_f32 v[32:33], v[44:45], v[66:67] op_sel_hi:[1,0]
	v_pk_mul_f32 v[34:35], v[46:47], v[66:67] op_sel_hi:[1,0]
	global_store_dwordx2 v[68:69], v[16:17], off offset:160
	v_pk_mul_f32 v[16:17], v[28:29], v[66:67] op_sel_hi:[1,0]
	v_pk_mul_f32 v[18:19], v[30:31], v[66:67] op_sel_hi:[1,0]
	global_store_dwordx2 v[68:69], v[0:1], off offset:224
	v_pk_mul_f32 v[0:1], v[12:13], v[66:67] op_sel_hi:[1,0]
	v_pk_mul_f32 v[2:3], v[14:15], v[66:67] op_sel_hi:[1,0]
	v_cvt_pk_bf16_f32 v48, v48, v49
	v_cvt_pk_bf16_f32 v49, v50, v51
	v_cvt_pk_bf16_f32 v32, v32, v33
	v_cvt_pk_bf16_f32 v33, v34, v35
	v_cvt_pk_bf16_f32 v16, v16, v17
	v_cvt_pk_bf16_f32 v17, v18, v19
	v_cvt_pk_bf16_f32 v0, v0, v1
	v_cvt_pk_bf16_f32 v1, v2, v3
	global_store_dwordx2 v[68:69], v[48:49], off offset:48
	global_store_dwordx2 v[68:69], v[32:33], off offset:112
	global_store_dwordx2 v[68:69], v[16:17], off offset:176
	global_store_dwordx2 v[68:69], v[0:1], off offset:240
	s_barrier

; __device__ __forceinline__ void mla_phase(KP p, LAS unsigned char* lds, int wv0) {
;     ...
;   for (int k = 0; k * G < 1024; ++k) {
;     const int idx = (k & 1) ? (G - 1 - bid) : bid, rank = k * G + idx;
;     if (rank >= 1024) continue;
;     const int qb = 15 - rank / 64, bh = rank % 64, b = bh >> 4, hd = bh & 15;
;     const int tok0 = b * SEQ, q0 = qb * 256 + 32 * wid;
;     bf16x8 qf[12];
;     { const bf16_t* qrow = q + (size_t)(tok0 + q0 + c) * NQ + hd * 192 + 8 * hh;
; #pragma unroll
;       for (int st = 0; st < 12; ++st) qf[st] = *(const bf16x8*)(qrow + 16 * st); }
;     f32x16 o[4];
; #pragma unroll
;     for (int d = 0; d < 4; ++d)
; #pragma unroll
;       for (int r = 0; r < 16; ++r) o[d][r] = 0.f;
;     float m = -1e30f, l = 0.f;
;     const int ntiles = qb * 4 + 4;
;     unsigned ksrc[3]; int kdst[3];
;     const unsigned char* wsb = p->ws;
; #pragma unroll
;     for (int i = 0; i < 3; ++i) { const int cid = tid + 512 * i, key = cid / 24, ch = cid % 24;
;       ksrc[i] = (ch < 16) ? (unsigned)(O_KV + ((size_t)(tok0 + key) * NKV + hd * 256 + ch * 8) * 2) : (unsigned)(O_H + ((size_t)(tok0 + key) * LDH + C_KR + (ch - 16) * 8) * 2);
;       kdst[i] = key * KSTR + ch * 16; }
;     const unsigned kinc0 = 64u * NKV * 2u, kinc1 = 64u * LDH * 2u;
;     const bool k2rope = ((tid + 1024) % 24) >= 16, k1rope = ((tid + 512) % 24) >= 16, k0rope = (tid % 24) >= 16;
;     unsigned vsrc[2]; int vdst[2];
; #pragma unroll
;     for (int i = 0; i < 2; ++i) { const int cid = tid + 512 * i, key = cid >> 4, ch = cid & 15;
;       vsrc[i] = (unsigned)(O_KV + ((size_t)(tok0 + key) * NKV + hd * 256 + 128 + ch * 8) * 2); vdst[i] = key * VSTR + ch * 16; }
;     u32x4 kr0 = *(const u32x4*)(wsb + ksrc[0]), kr1 = *(const u32x4*)(wsb + ksrc[1]), kr2 = *(const u32x4*)(wsb + ksrc[2]), vr0 = *(const u32x4*)(wsb + vsrc[0]), vr1 = *(const u32x4*)(wsb + vsrc[1]);
.LBB0_823:
	s_bitcmp0_b32 s21, 0
	s_cselect_b32 s1, s18, s19
	s_add_i32 s1, s1, s0
	s_cmpk_gt_i32 s1, 0x3ff
	s_cbranch_scc1 .LBB0_822
	s_ashr_i32 s0, s1, 31
	s_lshr_b32 s0, s0, 26
	s_add_i32 s8, s1, s0
	s_ashr_i32 s0, s8, 6
	s_andn2_b32 s8, s8, 63
	s_sub_i32 s0, 15, s0
	s_sub_i32 s8, s1, s8
	s_and_b32 s1, s8, 15
	s_lshl_b32 s8, s8, 8
	s_lshl_b32 s22, s0, 8
	s_and_b32 s10, s8, 0xfffff000
	s_add_i32 s22, s22, s20
	s_add_i32 s8, s22, s10
	v_or_b32_e32 v215, s8, v181
	v_mov_b64_e32 v[0:1], s[14:15]
	v_mad_i64_i32 v[0:1], s[8:9], v215, s83, v[0:1]
	s_mul_i32 s92, s1, 0x180
	v_lshl_add_u64 v[0:1], v[0:1], 0, s[92:93]
	v_mov_b32_e32 v189, v97
	v_lshl_add_u64 v[0:1], v[0:1], 0, v[188:189]
	global_load_dwordx4 v[112:115], v[0:1], off
	global_load_dwordx4 v[116:119], v[0:1], off offset:32
	global_load_dwordx4 v[120:123], v[0:1], off offset:64
	global_load_dwordx4 v[124:127], v[0:1], off offset:96
	global_load_dwordx4 v[128:131], v[0:1], off offset:128
	global_load_dwordx4 v[132:135], v[0:1], off offset:160
	global_load_dwordx4 v[136:139], v[0:1], off offset:192
	global_load_dwordx4 v[140:143], v[0:1], off offset:224
	global_load_dwordx4 v[144:147], v[0:1], off offset:256
	global_load_dwordx4 v[148:151], v[0:1], off offset:288
	global_load_dwordx4 v[152:155], v[0:1], off offset:320
	global_load_dwordx4 v[156:159], v[0:1], off offset:352
	v_add_u32_e32 v0, s10, v187
	s_and_saveexec_b64 s[8:9], s[2:3]
	s_xor_b64 s[8:9], exec, s[8:9]
	v_mad_u64_u32 v[190:191], s[24:25], v0, s91, v[182:183]
	s_or_saveexec_b64 s[8:9], s[8:9]
	s_lshl_b32 s11, s1, 9
	s_or_b32 s23, s11, 0x1f300000
	s_xor_b64 exec, exec, s[8:9]
	v_lshlrev_b32_e32 v0, 13, v0
	v_add3_u32 v190, s23, v204, v0
	s_or_b64 exec, exec, s[8:9]
	v_add_u32_e32 v0, s10, v185
	s_and_saveexec_b64 s[8:9], s[4:5]
	s_xor_b64 s[8:9], exec, s[8:9]
	v_mad_u64_u32 v[192:193], s[24:25], v0, s91, v[184:185]
	s_andn2_saveexec_b64 s[8:9], s[8:9]
	v_lshlrev_b32_e32 v0, 13, v0
	v_add3_u32 v192, s23, v206, v0
	s_or_b64 exec, exec, s[8:9]
	v_add_u32_e32 v0, s10, v183
	s_and_saveexec_b64 s[8:9], s[6:7]
	s_xor_b64 s[8:9], exec, s[8:9]
	v_mad_u64_u32 v[194:195], s[24:25], v0, s91, v[186:187]
	s_andn2_saveexec_b64 s[8:9], s[8:9]
	v_lshlrev_b32_e32 v0, 13, v0
	v_add3_u32 v194, s23, v208, v0
	s_or_b64 exec, exec, s[8:9]
	v_or_b32_e32 v0, s11, v214
	v_add_u32_e32 v1, s10, v210
	v_lshl_add_u32 v189, v1, 13, v0
	v_add_u32_e32 v1, s10, v212
	v_lshl_add_u32 v191, v1, 13, v0
	v_mov_b32_e32 v96, v97
	s_lshl_b32 s23, s0, 2
	v_or_b32_e32 v193, s22, v181
	s_waitcnt vmcnt(20)
	v_mov_b32_e32 v98, v97
	v_mov_b32_e32 v99, v97
	v_mov_b32_e32 v100, v97
	v_mov_b32_e32 v101, v97
	v_mov_b32_e32 v102, v97
	v_mov_b32_e32 v103, v97
	v_mov_b32_e32 v104, v97
	v_mov_b32_e32 v105, v97
	v_mov_b32_e32 v106, v97
	v_mov_b32_e32 v107, v97
	v_mov_b32_e32 v108, v97
	v_mov_b32_e32 v109, v97
	v_mov_b32_e32 v110, v97
	v_mov_b32_e32 v111, v97
	v_mov_b64_e32 v[48:49], v[96:97]
	v_mov_b64_e32 v[32:33], v[96:97]
	v_mov_b64_e32 v[16:17], v[96:97]
	v_mov_b64_e32 v[0:1], v[96:97]
	s_add_i32 s23, s23, 4
	s_or_b32 s24, s22, 31
	v_add_u32_e32 v195, -2.0, v193
	s_mov_b32 s25, 0
	v_mov_b32_e32 v217, 0xf149f2ca
	v_mov_b32_e32 v216, 0
	s_mov_b32 s26, 63
	v_mov_b64_e32 v[50:51], v[98:99]
	v_mov_b64_e32 v[52:53], v[100:101]
	v_mov_b64_e32 v[54:55], v[102:103]
	v_mov_b64_e32 v[56:57], v[104:105]
	v_mov_b64_e32 v[58:59], v[106:107]
	v_mov_b64_e32 v[60:61], v[108:109]
	v_mov_b64_e32 v[62:63], v[110:111]
	v_mov_b64_e32 v[34:35], v[98:99]
	v_mov_b64_e32 v[36:37], v[100:101]
	v_mov_b64_e32 v[38:39], v[102:103]
	v_mov_b64_e32 v[40:41], v[104:105]
	v_mov_b64_e32 v[42:43], v[106:107]
	v_mov_b64_e32 v[44:45], v[108:109]
	v_mov_b64_e32 v[46:47], v[110:111]
	v_mov_b64_e32 v[18:19], v[98:99]
	v_mov_b64_e32 v[20:21], v[100:101]
	v_mov_b64_e32 v[22:23], v[102:103]
	v_mov_b64_e32 v[24:25], v[104:105]
	v_mov_b64_e32 v[26:27], v[106:107]
	v_mov_b64_e32 v[28:29], v[108:109]
	v_mov_b64_e32 v[30:31], v[110:111]
	v_mov_b64_e32 v[2:3], v[98:99]
	v_mov_b64_e32 v[4:5], v[100:101]
	v_mov_b64_e32 v[6:7], v[102:103]
	v_mov_b64_e32 v[8:9], v[104:105]
	v_mov_b64_e32 v[10:11], v[106:107]
	v_mov_b64_e32 v[12:13], v[108:109]
	v_mov_b64_e32 v[14:15], v[110:111]
.Lmla_entry:
	s_lshr_b32 s63, s10, 6
	s_lshl_b32 s64, s1, 9
	v_mov_b32_e32 v111, s64
	v_mad_u32_u24 v198, v210, s63, v204
	v_mad_u32_u24 v199, v211, s63, v205
	v_mad_u32_u24 v176, v212, s63, v206
	v_mad_u32_u24 v177, v213, s63, v207
	v_mad_u32_u24 v178, v196, s63, v208
	v_mad_u32_u24 v179, v197, s63, v209
	v_cmp_eq_u32_e32 vcc, 0x80000, v210
	s_nop 1
	v_cndmask_b32_e32 v252, 0, v111, vcc
	v_add_u32_e32 v198, v198, v252
	v_cmp_eq_u32_e32 vcc, 0x80000, v211
	s_nop 1
	v_cndmask_b32_e32 v252, 0, v111, vcc
	v_add_u32_e32 v199, v199, v252
	v_cmp_eq_u32_e32 vcc, 0x80000, v212
	s_nop 1
	v_cndmask_b32_e32 v252, 0, v111, vcc
	v_add_u32_e32 v176, v176, v252
	v_cmp_eq_u32_e32 vcc, 0x80000, v213
	s_nop 1
	v_cndmask_b32_e32 v252, 0, v111, vcc
	v_add_u32_e32 v177, v177, v252
	v_cmp_eq_u32_e32 vcc, 0x80000, v196
	s_nop 1
	v_cndmask_b32_e32 v252, 0, v111, vcc
	v_add_u32_e32 v178, v178, v252
	v_cmp_eq_u32_e32 vcc, 0x80000, v197
	s_nop 1
	v_cndmask_b32_e32 v252, 0, v111, vcc
	v_add_u32_e32 v179, v179, v252
	s_mov_b32 s28, 0
	s_mov_b32 s29, s23
	s_lshr_b32 s30, s22, 5
	s_mov_b32 s32, 0
	s_mov_b32 s34, 0xc800
	s_mov_b32 s35, 0xc800
	s_mov_b32 s36, 0x11800
	s_mov_b32 s63, 0
	s_mov_b32 s64, 0xc800
; #define LAS __attribute__((address_space(3)))
; template <int NQK, int NDV, int KSTR, int VSTR> ...
;     ...
;   if (domask) {
; #pragma unroll
;     for (int r = 0; r < 16; ++r) { const int kp = kpos0 + (r & 3) + 8 * (r >> 2) + 4 * h;
;       const bool v0 = (kp <= qpos) && (kp > qpos - window) && (kp >= 0);
;       const bool v1 = (kp + 32 <= qpos) && (kp + 32 > qpos - window) && (kp + 32 >= 0);
;       s0[r] = v0 ? s0[r] : -1e30f; s1[r] = v1 ? s1[r] : -1e30f; }
;   }
;   float mx = fmaxf(s0[0], s1[0]);
; #pragma unroll
;   for (int r = 1; r < 16; ++r) mx = fmaxf(mx, fmaxf(s0[r], s1[r]));
;   mx = fmaxf(mx, __shfl_xor(mx, 32));
;   if (__builtin_amdgcn_ballot_w64(mx > m + 8.0f) != 0ull) {
; __device__ __forceinline__ void mla_phase(KP p, LAS unsigned char* lds, int wv0) {
;     ...
;     for (int kt = 0; kt < ntiles; ++kt) {
;       LAS unsigned char* Kb = lds + (kt & 1) * KB; LAS unsigned char* Vb = lds + 2 * KB + (kt & 1) * VB;
;       *(LAS u32x4*)(Kb + kdst[0]) = kr0; *(LAS u32x4*)(Kb + kdst[1]) = kr1; *(LAS u32x4*)(Kb + kdst[2]) = kr2;
;       *(LAS u32x4*)(Vb + vdst[0]) = vr0; *(LAS u32x4*)(Vb + vdst[1]) = vr1;
;       __syncthreads();
;       if (kt + 1 < ntiles) {
;         ksrc[0] += k0rope ? kinc1 : kinc0; ksrc[1] += k1rope ? kinc1 : kinc0; ksrc[2] += k2rope ? kinc1 : kinc0; vsrc[0] += kinc0; vsrc[1] += kinc0;
;         kr0 = *(const u32x4*)(wsb + ksrc[0]); kr1 = *(const u32x4*)(wsb + ksrc[1]); kr2 = *(const u32x4*)(wsb + ksrc[2]); vr0 = *(const u32x4*)(wsb + vsrc[0]); vr1 = *(const u32x4*)(wsb + vsrc[1]);
;       }
.Lmla_dma0:
	s_add_u32 m0, s63, s48
	s_nop 0
	global_load_lds_dwordx4 v198, s[12:13]
	v_add_u32_e32 v198, v198, v210
	s_add_u32 m0, s63, s49
	s_nop 0
	global_load_lds_dwordx4 v199, s[12:13]
	v_add_u32_e32 v199, v199, v211
	s_add_u32 m0, s63, s50
	s_nop 0
	global_load_lds_dwordx4 v176, s[12:13]
	v_add_u32_e32 v176, v176, v212
	s_add_u32 m0, s64, s51
	s_nop 0
	global_load_lds_dwordx4 v177, s[12:13]
	v_add_u32_e32 v177, v177, v213
	s_add_u32 m0, s64, s52
	s_nop 0
	global_load_lds_dwordx4 v178, s[12:13]
	v_add_u32_e32 v178, v178, v196
	s_cmp_eq_u32 s58, 0
	s_cbranch_scc1 .Lmla_no6a
	s_cmp_eq_u32 s58, 1
	s_cselect_b32 s65, s63, s64
	s_add_u32 m0, s65, s56
	s_nop 0
	global_load_lds_dwordx4 v179, s[12:13]
	v_add_u32_e32 v179, v179, v197
.Lmla_no6a:
.Lmla_iter:
	s_cmp_ge_u32 s28, s29
	s_cbranch_scc1 .Lmla_nostage
	s_waitcnt vmcnt(0)
	s_barrier
	s_add_u32 s37, s28, 1
	s_cmp_ge_u32 s37, s29
	s_cbranch_scc1 .Lmla_noload
	s_xor_b32 s63, s32, 0x6400
	s_mov_b32 s64, s36
	s_add_u32 m0, s63, s48
	s_nop 0
	global_load_lds_dwordx4 v198, s[12:13]
	v_add_u32_e32 v198, v198, v210
	s_add_u32 m0, s63, s49
	s_nop 0
	global_load_lds_dwordx4 v199, s[12:13]
	v_add_u32_e32 v199, v199, v211
	s_add_u32 m0, s63, s50
	s_nop 0
	global_load_lds_dwordx4 v176, s[12:13]
	v_add_u32_e32 v176, v176, v212
	s_add_u32 m0, s64, s51
	s_nop 0
	global_load_lds_dwordx4 v177, s[12:13]
	v_add_u32_e32 v177, v177, v213
	s_add_u32 m0, s64, s52
	s_nop 0
	global_load_lds_dwordx4 v178, s[12:13]
	v_add_u32_e32 v178, v178, v196
	s_cmp_eq_u32 s58, 0
	s_cbranch_scc1 .Lmla_no6b
	s_cmp_eq_u32 s58, 1
	s_cselect_b32 s65, s63, s64
	s_add_u32 m0, s65, s56
	s_nop 0
	global_load_lds_dwordx4 v179, s[12:13]
	v_add_u32_e32 v179, v179, v197
.Lmla_no6b:
.Lmla_noload:
.Lmla_nostage:
	v_add3_u32 v96, s32, v200, v201
	v_add3_u32 v110, s35, v202, v203
	s_lshl_b32 s31, s28, 1
	s_sub_u32 s37, s31, 1
	s_cmp_eq_u32 s28, 0
	s_cbranch_scc1 .Lmla_s1_done
	s_cmp_le_u32 s37, s30
	s_cbranch_scc1 .Lmla_Yfo
	s_add_u32 s47, s30, 1
	s_cmp_eq_u32 s37, s47
	s_cbranch_scc1 .Lmla_Ypo
	s_branch .Lmla_s1_done
.Lmla_Yfo:
	ds_read_b64_tr_b16 v[234:235], v110 offset:5120
	ds_read_b64_tr_b16 v[236:237], v110 offset:7680
	ds_read_b64_tr_b16 v[238:239], v110 offset:5184
	ds_read_b64_tr_b16 v[240:241], v110 offset:7744
	ds_read_b64_tr_b16 v[242:243], v110 offset:5248
	ds_read_b64_tr_b16 v[244:245], v110 offset:7808
	ds_read_b64_tr_b16 v[246:247], v110 offset:5312
	ds_read_b64_tr_b16 v[248:249], v110 offset:7872
	s_waitcnt lgkmcnt(8)
	v_mfma_f32_32x32x16_bf16 v[48:63], v[218:221], v[80:83], v[48:63]
	v_mfma_f32_32x32x16_bf16 v[32:47], v[222:225], v[80:83], v[32:47]
	v_mfma_f32_32x32x16_bf16 v[16:31], v[226:229], v[80:83], v[16:31]
	v_mfma_f32_32x32x16_bf16 v[0:15], v[230:233], v[80:83], v[0:15]
	s_cmp_lg_u32 s37, s30
	s_cbranch_scc1 .Lmla_Yfo_nomask
	v_mov_b32_e32 v253, 0xf149f2ca
	v_sub_u32_e32 v111, v181, v180
	v_cmp_le_i32_e64 s[38:39], 0, v111
	v_cmp_le_i32_e64 s[40:41], 1, v111
	v_cmp_le_i32_e64 s[42:43], 2, v111
	v_cmp_le_i32_e64 s[44:45], 3, v111
	v_cndmask_b32_e64 v64, v253, v64, s[38:39]
	v_cndmask_b32_e64 v65, v253, v65, s[40:41]
	v_cndmask_b32_e64 v66, v253, v66, s[42:43]
	v_cndmask_b32_e64 v67, v253, v67, s[44:45]
	v_cmp_le_i32_e64 s[38:39], 8, v111
	v_cmp_le_i32_e64 s[40:41], 9, v111
	v_cmp_le_i32_e64 s[42:43], 10, v111
	v_cmp_le_i32_e64 s[44:45], 11, v111
	v_cndmask_b32_e64 v68, v253, v68, s[38:39]
	v_cndmask_b32_e64 v69, v253, v69, s[40:41]
	v_cndmask_b32_e64 v70, v253, v70, s[42:43]
	v_cndmask_b32_e64 v71, v253, v71, s[44:45]
	v_cmp_le_i32_e64 s[38:39], 16, v111
	v_cmp_le_i32_e64 s[40:41], 17, v111
	v_cmp_le_i32_e64 s[42:43], 18, v111
	v_cmp_le_i32_e64 s[44:45], 19, v111
	v_cndmask_b32_e64 v72, v253, v72, s[38:39]
	v_cndmask_b32_e64 v73, v253, v73, s[40:41]
	v_cndmask_b32_e64 v74, v253, v74, s[42:43]
	v_cndmask_b32_e64 v75, v253, v75, s[44:45]
	v_cmp_le_i32_e64 s[38:39], 24, v111
	v_cmp_le_i32_e64 s[40:41], 25, v111
	v_cmp_le_i32_e64 s[42:43], 26, v111
	v_cmp_le_i32_e64 s[44:45], 27, v111
	v_cndmask_b32_e64 v76, v253, v76, s[38:39]
	v_cndmask_b32_e64 v77, v253, v77, s[40:41]
	v_cndmask_b32_e64 v78, v253, v78, s[42:43]
	v_cndmask_b32_e64 v79, v253, v79, s[44:45]
.Lmla_Yfo_nomask:
	s_waitcnt lgkmcnt(0)
	v_mfma_f32_32x32x16_bf16 v[48:63], v[234:237], v[84:87], v[48:63]
	v_max3_f32 v111, v64, v65, v66
	v_max3_f32 v111, v111, v67, v68
	v_mfma_f32_32x32x16_bf16 v[32:47], v[238:241], v[84:87], v[32:47]
	v_max3_f32 v111, v111, v69, v70
	v_max3_f32 v111, v111, v71, v72
	v_mfma_f32_32x32x16_bf16 v[16:31], v[242:245], v[84:87], v[16:31]
	v_max3_f32 v111, v111, v73, v74
	v_max3_f32 v111, v111, v75, v76
	v_mfma_f32_32x32x16_bf16 v[0:15], v[246:249], v[84:87], v[0:15]
	v_max3_f32 v111, v111, v77, v78
	v_max_f32_e32 v111, v111, v79
	s_cmp_ge_u32 s37, s30
	s_cbranch_scc1 .Lmla_Yfo_nokpf
	ds_read_b128 v[98:101], v96 offset:0
	ds_read_b128 v[102:105], v96 offset:32
	ds_read_b128 v[106:109], v96 offset:64
.Lmla_Yfo_nokpf:
	v_mov_b32_e32 v252, v111
	s_nop 1
	v_permlane32_swap_b32_e32 v111, v252
	s_nop 0
	v_max_f32_e32 v111, v111, v252
	s_nop 0
	v_cmp_lt_f32_e32 vcc, 0x41000000, v111
	s_cbranch_vccnz .Lmla_rescale1

; #define LAS __attribute__((address_space(3)))
; __device__ __forceinline__ float fexp2(float x) { return __builtin_amdgcn_exp2f(x); }
; __device__ __forceinline__ f32x16 mfma32(bf16x8 a, bf16x8 b, f32x16 c) { return __builtin_amdgcn_mfma_f32_32x32x16_bf16(a, b, c, 0, 0, 0); }
; template <int NQK, int NDV, int KSTR, int VSTR> ...
;     ...
;   const LAS unsigned char* ka = Kt + c * KSTR + h * 16;
;   bf16x8 kc0 = *(const LAS bf16x8*)(ka), kc1 = *(const LAS bf16x8*)(ka + 32 * KSTR);
; #pragma unroll
;   for (int st = 0; st < NQK; ++st) {
;     bf16x8 kn0 = kc0, kn1 = kc1;
;     if (st + 1 < NQK) { kn0 = *(const LAS bf16x8*)(ka + (st + 1) * 32); kn1 = *(const LAS bf16x8*)(ka + 32 * KSTR + (st + 1) * 32); }
;     s0 = mfma32(kc0, qf[st], s0);
;     s1 = mfma32(kc1, qf[st], s1);
;     if (st + 1 < NQK) __builtin_amdgcn_sched_group_barrier(0x100, 2, 0);
;     __builtin_amdgcn_sched_group_barrier(0x008, 2, 0);
;     kc0 = kn0; kc1 = kn1;
;   }
;   if (domask) {
; #pragma unroll
;     for (int r = 0; r < 16; ++r) { const int kp = kpos0 + (r & 3) + 8 * (r >> 2) + 4 * h;
;       const bool v0 = (kp <= qpos) && (kp > qpos - window) && (kp >= 0);
;       const bool v1 = (kp + 32 <= qpos) && (kp + 32 > qpos - window) && (kp + 32 >= 0);
;       s0[r] = v0 ? s0[r] : -1e30f; s1[r] = v1 ? s1[r] : -1e30f; }
;   }
;   float mx = fmaxf(s0[0], s1[0]);
; #pragma unroll
;   for (int r = 1; r < 16; ++r) mx = fmaxf(mx, fmaxf(s0[r], s1[r]));
;   mx = fmaxf(mx, __shfl_xor(mx, 32));
;   if (__builtin_amdgcn_ballot_w64(mx > m + 8.0f) != 0ull) {
;     const float mn = fmaxf(m, mx), alpha = fexp2(m - mn);
;     m = mn; l *= alpha;
; #pragma unroll
;     for (int d = 0; d < NDV; ++d) o[d] *= alpha;
;   }
;   float ps = 0.f;
; #pragma unroll
;   for (int r = 0; r < 16; ++r) { s0[r] = fexp2(s0[r] - m); s1[r] = fexp2(s1[r] - m); ps += s0[r] + s1[r]; }
;   l += ps;
;   bf16x8 pf[4];
; #pragma unroll
;   for (int s = 0; s < 2; ++s) {
;     u32x4 w0, w1;
;     w0.x = pk2(s0[8 * s + 0], s0[8 * s + 1]); w0.y = pk2(s0[8 * s + 2], s0[8 * s + 3]); w0.z = pk2(s0[8 * s + 4], s0[8 * s + 5]); w0.w = pk2(s0[8 * s + 6], s0[8 * s + 7]);
;     w1.x = pk2(s1[8 * s + 0], s1[8 * s + 1]); w1.y = pk2(s1[8 * s + 2], s1[8 * s + 3]); w1.z = pk2(s1[8 * s + 4], s1[8 * s + 5]); w1.w = pk2(s1[8 * s + 6], s1[8 * s + 7]);
;     pf[s] = __builtin_bit_cast(bf16x8, w0); pf[2 + s] = __builtin_bit_cast(bf16x8, w1);
;   }
.Lmla_Ypo:
	ds_read_b64_tr_b16 v[234:235], v110 offset:5120
	ds_read_b64_tr_b16 v[236:237], v110 offset:7680
	ds_read_b64_tr_b16 v[238:239], v110 offset:5184
	ds_read_b64_tr_b16 v[240:241], v110 offset:7744
	ds_read_b64_tr_b16 v[242:243], v110 offset:5248
	ds_read_b64_tr_b16 v[244:245], v110 offset:7808
	ds_read_b64_tr_b16 v[246:247], v110 offset:5312
	ds_read_b64_tr_b16 v[248:249], v110 offset:7872
	s_waitcnt lgkmcnt(8)
	v_mfma_f32_32x32x16_bf16 v[48:63], v[218:221], v[80:83], v[48:63]
	v_mfma_f32_32x32x16_bf16 v[32:47], v[222:225], v[80:83], v[32:47]
	v_mfma_f32_32x32x16_bf16 v[16:31], v[226:229], v[80:83], v[16:31]
	v_mfma_f32_32x32x16_bf16 v[0:15], v[230:233], v[80:83], v[0:15]
	s_waitcnt lgkmcnt(0)
	v_mfma_f32_32x32x16_bf16 v[48:63], v[234:237], v[84:87], v[48:63]
	v_mfma_f32_32x32x16_bf16 v[32:47], v[238:241], v[84:87], v[32:47]
	v_mfma_f32_32x32x16_bf16 v[16:31], v[242:245], v[84:87], v[16:31]
	v_mfma_f32_32x32x16_bf16 v[0:15], v[246:249], v[84:87], v[0:15]
.Lmla_s1_done:
	s_cmp_le_u32 s31, s30
	s_cbranch_scc0 .Lmla_s2_tail
	s_cmp_eq_u32 s31, 0
	s_cbranch_scc1 .Lmla_Xq
.Lmla_Xfe:
	s_waitcnt lgkmcnt(2)
	v_mfma_f32_32x32x16_bf16 v[80:95], v[98:101], v[112:115], v[160:175]
	ds_read_b128 v[98:101], v96 offset:96
	v_exp_f32_e32 v64, v64
	v_exp_f32_e32 v65, v65
	v_exp_f32_e32 v66, v66
	v_exp_f32_e32 v67, v67
	s_waitcnt lgkmcnt(2)
	v_mfma_f32_32x32x16_bf16 v[80:95], v[102:105], v[116:119], v[80:95]
	ds_read_b128 v[102:105], v96 offset:128
	v_add_f32_e32 v252, v64, v65
	v_exp_f32_e32 v68, v68
	v_exp_f32_e32 v69, v69
	v_add_f32_e32 v253, v66, v67
	s_waitcnt lgkmcnt(2)
	v_mfma_f32_32x32x16_bf16 v[80:95], v[106:109], v[120:123], v[80:95]
	ds_read_b128 v[106:109], v96 offset:160
	v_cvt_pk_bf16_f32 v64, v64, v65
	v_exp_f32_e32 v70, v70
	v_exp_f32_e32 v71, v71
	v_add_f32_e32 v252, v252, v68
	s_waitcnt lgkmcnt(2)
	v_mfma_f32_32x32x16_bf16 v[80:95], v[98:101], v[124:127], v[80:95]
	ds_read_b128 v[98:101], v96 offset:192
	v_add_f32_e32 v252, v252, v69
	v_cvt_pk_bf16_f32 v65, v66, v67
	v_exp_f32_e32 v72, v72
	v_exp_f32_e32 v73, v73
	s_waitcnt lgkmcnt(2)
	v_mfma_f32_32x32x16_bf16 v[80:95], v[102:105], v[128:131], v[80:95]
	ds_read_b128 v[102:105], v96 offset:224
	v_add_f32_e32 v253, v253, v70
	v_add_f32_e32 v253, v253, v71
	v_cvt_pk_bf16_f32 v66, v68, v69
	v_exp_f32_e32 v74, v74
	s_waitcnt lgkmcnt(2)
	v_mfma_f32_32x32x16_bf16 v[80:95], v[106:109], v[132:135], v[80:95]
	ds_read_b128 v[106:109], v96 offset:256
	v_exp_f32_e32 v75, v75
	v_add_f32_e32 v252, v252, v72
	v_add_f32_e32 v252, v252, v73
	s_waitcnt lgkmcnt(2)
	v_mfma_f32_32x32x16_bf16 v[80:95], v[98:101], v[136:139], v[80:95]
	ds_read_b128 v[98:101], v96 offset:288
	v_cvt_pk_bf16_f32 v67, v70, v71
	v_exp_f32_e32 v76, v76
	v_exp_f32_e32 v77, v77
	s_waitcnt lgkmcnt(2)
	v_mfma_f32_32x32x16_bf16 v[80:95], v[102:105], v[140:143], v[80:95]
	ds_read_b128 v[102:105], v96 offset:320
	v_add_f32_e32 v253, v253, v74
	v_add_f32_e32 v253, v253, v75
	v_cvt_pk_bf16_f32 v68, v72, v73
	s_waitcnt lgkmcnt(2)
	v_mfma_f32_32x32x16_bf16 v[80:95], v[106:109], v[144:147], v[80:95]
	ds_read_b128 v[106:109], v96 offset:352
	ds_read_b64_tr_b16 v[218:219], v110 offset:10240
	ds_read_b64_tr_b16 v[220:221], v110 offset:12800
	ds_read_b64_tr_b16 v[222:223], v110 offset:10304
	ds_read_b64_tr_b16 v[224:225], v110 offset:12864
	ds_read_b64_tr_b16 v[226:227], v110 offset:10368
	ds_read_b64_tr_b16 v[228:229], v110 offset:12928
	ds_read_b64_tr_b16 v[230:231], v110 offset:10432
	ds_read_b64_tr_b16 v[232:233], v110 offset:12992
	v_exp_f32_e32 v78, v78
	v_exp_f32_e32 v79, v79
	v_add_f32_e32 v252, v252, v76
	s_waitcnt lgkmcnt(10)
	v_mfma_f32_32x32x16_bf16 v[80:95], v[98:101], v[148:151], v[80:95]
	v_add_f32_e32 v252, v252, v77
	v_cvt_pk_bf16_f32 v69, v74, v75
	s_nop 0
	s_waitcnt lgkmcnt(9)
	v_mfma_f32_32x32x16_bf16 v[80:95], v[102:105], v[152:155], v[80:95]
	v_add_f32_e32 v253, v253, v78
	v_add_f32_e32 v253, v253, v79
	v_cvt_pk_bf16_f32 v70, v76, v77
	s_waitcnt lgkmcnt(8)
	v_mfma_f32_32x32x16_bf16 v[80:95], v[106:109], v[156:159], v[80:95]
	v_cvt_pk_bf16_f32 v71, v78, v79
	v_add_f32_e32 v252, v252, v253
	v_add_f32_e32 v216, v216, v252
	s_branch .Lmla_s2_done
.Lmla_Xq:
	ds_read_b128 v[98:101], v96 offset:0
	ds_read_b128 v[102:105], v96 offset:32
	ds_read_b128 v[106:109], v96 offset:64
	s_waitcnt lgkmcnt(2)
	v_mfma_f32_32x32x16_bf16 v[80:95], v[98:101], v[112:115], 0
	ds_read_b128 v[98:101], v96 offset:96
	s_waitcnt lgkmcnt(2)
	v_mfma_f32_32x32x16_bf16 v[80:95], v[102:105], v[116:119], v[80:95]
	ds_read_b128 v[102:105], v96 offset:128
	s_waitcnt lgkmcnt(2)
	v_mfma_f32_32x32x16_bf16 v[80:95], v[106:109], v[120:123], v[80:95]
	ds_read_b128 v[106:109], v96 offset:160
	s_waitcnt lgkmcnt(2)
	v_mfma_f32_32x32x16_bf16 v[80:95], v[98:101], v[124:127], v[80:95]
	ds_read_b128 v[98:101], v96 offset:192
	s_waitcnt lgkmcnt(2)
	v_mfma_f32_32x32x16_bf16 v[80:95], v[102:105], v[128:131], v[80:95]
	ds_read_b128 v[102:105], v96 offset:224
	s_waitcnt lgkmcnt(2)
	v_mfma_f32_32x32x16_bf16 v[80:95], v[106:109], v[132:135], v[80:95]
	ds_read_b128 v[106:109], v96 offset:256
	s_waitcnt lgkmcnt(2)
	v_mfma_f32_32x32x16_bf16 v[80:95], v[98:101], v[136:139], v[80:95]
	ds_read_b128 v[98:101], v96 offset:288
	s_waitcnt lgkmcnt(2)
	v_mfma_f32_32x32x16_bf16 v[80:95], v[102:105], v[140:143], v[80:95]
	ds_read_b128 v[102:105], v96 offset:320
	s_waitcnt lgkmcnt(2)
	v_mfma_f32_32x32x16_bf16 v[80:95], v[106:109], v[144:147], v[80:95]
	ds_read_b128 v[106:109], v96 offset:352
	s_waitcnt lgkmcnt(2)
	v_mfma_f32_32x32x16_bf16 v[80:95], v[98:101], v[148:151], v[80:95]
	s_waitcnt lgkmcnt(1)
	v_mfma_f32_32x32x16_bf16 v[80:95], v[102:105], v[152:155], v[80:95]
	s_waitcnt lgkmcnt(0)
	v_mfma_f32_32x32x16_bf16 v[80:95], v[106:109], v[156:159], v[80:95]
	s_branch .Lmla_s2_done
; template <int NQK, int NDV, int KSTR, int VSTR> ...
;     ...
;   if (domask) {
; #pragma unroll
;     for (int r = 0; r < 16; ++r) { const int kp = kpos0 + (r & 3) + 8 * (r >> 2) + 4 * h;
;       const bool v0 = (kp <= qpos) && (kp > qpos - window) && (kp >= 0);
;       const bool v1 = (kp + 32 <= qpos) && (kp + 32 > qpos - window) && (kp + 32 >= 0);
;       s0[r] = v0 ? s0[r] : -1e30f; s1[r] = v1 ? s1[r] : -1e30f; }
;   }
;   float mx = fmaxf(s0[0], s1[0]);
; #pragma unroll
;   for (int r = 1; r < 16; ++r) mx = fmaxf(mx, fmaxf(s0[r], s1[r]));
;   mx = fmaxf(mx, __shfl_xor(mx, 32));
;   if (__builtin_amdgcn_ballot_w64(mx > m + 8.0f) != 0ull) {
;     const float mn = fmaxf(m, mx), alpha = fexp2(m - mn);
;     m = mn; l *= alpha;
; #pragma unroll
;     for (int d = 0; d < NDV; ++d) o[d] *= alpha;
;   }
;   float ps = 0.f;
; #pragma unroll
;   for (int r = 0; r < 16; ++r) { s0[r] = fexp2(s0[r] - m); s1[r] = fexp2(s1[r] - m); ps += s0[r] + s1[r]; }
;   l += ps;
;   bf16x8 pf[4];
; #pragma unroll
;   for (int s = 0; s < 2; ++s) {
;     u32x4 w0, w1;
;     w0.x = pk2(s0[8 * s + 0], s0[8 * s + 1]); w0.y = pk2(s0[8 * s + 2], s0[8 * s + 3]); w0.z = pk2(s0[8 * s + 4], s0[8 * s + 5]); w0.w = pk2(s0[8 * s + 6], s0[8 * s + 7]);
;     w1.x = pk2(s1[8 * s + 0], s1[8 * s + 1]); w1.y = pk2(s1[8 * s + 2], s1[8 * s + 3]); w1.z = pk2(s1[8 * s + 4], s1[8 * s + 5]); w1.w = pk2(s1[8 * s + 6], s1[8 * s + 7]);
;     pf[s] = __builtin_bit_cast(bf16x8, w0); pf[2 + s] = __builtin_bit_cast(bf16x8, w1);
;   }
;   const int i16 = lane & 15, g16 = (lane >> 4) & 1;
;   const LAS unsigned char* va = Vt + (4 * h + (i16 >> 2)) * VSTR + (16 * g16 + 4 * (i16 & 3)) * 2;
;   bf16x8 vc[NDV];
; #pragma unroll
;   for (int d = 0; d < NDV; ++d) { const v4i16_t lo = vtr(va + d * 64), hi = vtr(va + 8 * VSTR + d * 64); vc[d] = __builtin_shufflevector(lo, hi, 0, 1, 2, 3, 4, 5, 6, 7); }
; #pragma unroll
;   for (int ks = 0; ks < 4; ++ks) {
;     bf16x8 vn[NDV];
; #pragma unroll
;     for (int d = 0; d < NDV; ++d) { vn[d] = vc[d];
;       if (ks + 1 < 4) { const v4i16_t lo = vtr(va + (16 * (ks + 1)) * VSTR + d * 64), hi = vtr(va + (16 * (ks + 1) + 8) * VSTR + d * 64); vn[d] = __builtin_shufflevector(lo, hi, 0, 1, 2, 3, 4, 5, 6, 7); } }
; #pragma unroll
;     for (int d = 0; d < NDV; ++d) o[d] = mfma32(vc[d], pf[ks], o[d]);
;     if (ks + 1 < 4) __builtin_amdgcn_sched_group_barrier(0x100, 2 * NDV, 0);
.Lmla_s2_tail:
	s_add_u32 s47, s30, 1
	s_cmp_eq_u32 s31, s47
	s_cbranch_scc0 .Lmla_s2_done
.Lmla_Xse:
	v_exp_f32_e32 v64, v64
	v_exp_f32_e32 v65, v65
	v_exp_f32_e32 v66, v66
	v_exp_f32_e32 v67, v67
	v_add_f32_e32 v252, v64, v65
	v_exp_f32_e32 v68, v68
	v_exp_f32_e32 v69, v69
	v_add_f32_e32 v253, v66, v67
	v_cvt_pk_bf16_f32 v64, v64, v65
	v_exp_f32_e32 v70, v70
	v_exp_f32_e32 v71, v71
	v_add_f32_e32 v252, v252, v68
	v_add_f32_e32 v252, v252, v69
	v_cvt_pk_bf16_f32 v65, v66, v67
	v_exp_f32_e32 v72, v72
	v_exp_f32_e32 v73, v73
	v_add_f32_e32 v253, v253, v70
	v_add_f32_e32 v253, v253, v71
	v_cvt_pk_bf16_f32 v66, v68, v69
	v_exp_f32_e32 v74, v74
	v_exp_f32_e32 v75, v75
	v_add_f32_e32 v252, v252, v72
	v_add_f32_e32 v252, v252, v73
	v_cvt_pk_bf16_f32 v67, v70, v71
	v_exp_f32_e32 v76, v76
	v_exp_f32_e32 v77, v77
	v_add_f32_e32 v253, v253, v74
	v_add_f32_e32 v253, v253, v75
	v_cvt_pk_bf16_f32 v68, v72, v73
	v_exp_f32_e32 v78, v78
	v_exp_f32_e32 v79, v79
	v_add_f32_e32 v252, v252, v76
	v_add_f32_e32 v252, v252, v77
	v_cvt_pk_bf16_f32 v69, v74, v75
	s_nop 0
	v_add_f32_e32 v253, v253, v78
	v_add_f32_e32 v253, v253, v79
	v_cvt_pk_bf16_f32 v70, v76, v77
	v_cvt_pk_bf16_f32 v71, v78, v79
	v_add_f32_e32 v252, v252, v253
	v_add_f32_e32 v216, v216, v252
	ds_read_b64_tr_b16 v[218:219], v110 offset:10240
	ds_read_b64_tr_b16 v[220:221], v110 offset:12800
	ds_read_b64_tr_b16 v[222:223], v110 offset:10304
	ds_read_b64_tr_b16 v[224:225], v110 offset:12864
	ds_read_b64_tr_b16 v[226:227], v110 offset:10368
	ds_read_b64_tr_b16 v[228:229], v110 offset:12928
	ds_read_b64_tr_b16 v[230:231], v110 offset:10432
	ds_read_b64_tr_b16 v[232:233], v110 offset:12992
.Lmla_s2_done:
	s_mov_b32 s37, s31
	s_cmp_le_u32 s31, s30
	s_cbranch_scc0 .Lmla_s3_tail
	s_cmp_eq_u32 s31, 0
	s_cbranch_scc1 .Lmla_Ys
.Lmla_Yfe:
	ds_read_b64_tr_b16 v[234:235], v110 offset:15360
	ds_read_b64_tr_b16 v[236:237], v110 offset:17920
	ds_read_b64_tr_b16 v[238:239], v110 offset:15424
	ds_read_b64_tr_b16 v[240:241], v110 offset:17984
	ds_read_b64_tr_b16 v[242:243], v110 offset:15488
	ds_read_b64_tr_b16 v[244:245], v110 offset:18048
	ds_read_b64_tr_b16 v[246:247], v110 offset:15552
	ds_read_b64_tr_b16 v[248:249], v110 offset:18112
	s_waitcnt lgkmcnt(8)
	v_mfma_f32_32x32x16_bf16 v[48:63], v[218:221], v[64:67], v[48:63]
	v_mfma_f32_32x32x16_bf16 v[32:47], v[222:225], v[64:67], v[32:47]
	v_mfma_f32_32x32x16_bf16 v[16:31], v[226:229], v[64:67], v[16:31]
	v_mfma_f32_32x32x16_bf16 v[0:15], v[230:233], v[64:67], v[0:15]
	s_cmp_lg_u32 s37, s30
	s_cbranch_scc1 .Lmla_Yfe_nomask
	v_mov_b32_e32 v253, 0xf149f2ca
	v_sub_u32_e32 v111, v181, v180
	v_cmp_le_i32_e64 s[38:39], 0, v111
	v_cmp_le_i32_e64 s[40:41], 1, v111
	v_cmp_le_i32_e64 s[42:43], 2, v111
	v_cmp_le_i32_e64 s[44:45], 3, v111
	v_cndmask_b32_e64 v80, v253, v80, s[38:39]
	v_cndmask_b32_e64 v81, v253, v81, s[40:41]
	v_cndmask_b32_e64 v82, v253, v82, s[42:43]
	v_cndmask_b32_e64 v83, v253, v83, s[44:45]
	v_cmp_le_i32_e64 s[38:39], 8, v111
	v_cmp_le_i32_e64 s[40:41], 9, v111
	v_cmp_le_i32_e64 s[42:43], 10, v111
	v_cmp_le_i32_e64 s[44:45], 11, v111
	v_cndmask_b32_e64 v84, v253, v84, s[38:39]
	v_cndmask_b32_e64 v85, v253, v85, s[40:41]
	v_cndmask_b32_e64 v86, v253, v86, s[42:43]
	v_cndmask_b32_e64 v87, v253, v87, s[44:45]
	v_cmp_le_i32_e64 s[38:39], 16, v111
	v_cmp_le_i32_e64 s[40:41], 17, v111
	v_cmp_le_i32_e64 s[42:43], 18, v111
	v_cmp_le_i32_e64 s[44:45], 19, v111
	v_cndmask_b32_e64 v88, v253, v88, s[38:39]
	v_cndmask_b32_e64 v89, v253, v89, s[40:41]
	v_cndmask_b32_e64 v90, v253, v90, s[42:43]
	v_cndmask_b32_e64 v91, v253, v91, s[44:45]
	v_cmp_le_i32_e64 s[38:39], 24, v111
	v_cmp_le_i32_e64 s[40:41], 25, v111
	v_cmp_le_i32_e64 s[42:43], 26, v111
	v_cmp_le_i32_e64 s[44:45], 27, v111
	v_cndmask_b32_e64 v92, v253, v92, s[38:39]
	v_cndmask_b32_e64 v93, v253, v93, s[40:41]
	v_cndmask_b32_e64 v94, v253, v94, s[42:43]
	v_cndmask_b32_e64 v95, v253, v95, s[44:45]
.Lmla_Yfe_nomask:
	s_waitcnt lgkmcnt(0)
	v_mfma_f32_32x32x16_bf16 v[48:63], v[234:237], v[68:71], v[48:63]
	v_max3_f32 v111, v80, v81, v82
	v_max3_f32 v111, v111, v83, v84
	v_mfma_f32_32x32x16_bf16 v[32:47], v[238:241], v[68:71], v[32:47]
	v_max3_f32 v111, v111, v85, v86
	v_max3_f32 v111, v111, v87, v88
	v_mfma_f32_32x32x16_bf16 v[16:31], v[242:245], v[68:71], v[16:31]
	v_max3_f32 v111, v111, v89, v90
	v_max3_f32 v111, v111, v91, v92
	v_mfma_f32_32x32x16_bf16 v[0:15], v[246:249], v[68:71], v[0:15]
	v_max3_f32 v111, v111, v93, v94
	v_max_f32_e32 v111, v111, v95
	s_cmp_ge_u32 s37, s30
	s_cbranch_scc1 .Lmla_Yfe_nokpf
	ds_read_b128 v[98:101], v96 offset:12800
	ds_read_b128 v[102:105], v96 offset:12832
	ds_read_b128 v[106:109], v96 offset:12864

; __device__ __forceinline__ float fexp2(float x) { return __builtin_amdgcn_exp2f(x); }
; template <int NQK, int NDV, int KSTR, int VSTR> ...
;     ...
;   if (domask) {
; #pragma unroll
;     for (int r = 0; r < 16; ++r) { const int kp = kpos0 + (r & 3) + 8 * (r >> 2) + 4 * h;
;       const bool v0 = (kp <= qpos) && (kp > qpos - window) && (kp >= 0);
;       const bool v1 = (kp + 32 <= qpos) && (kp + 32 > qpos - window) && (kp + 32 >= 0);
;       s0[r] = v0 ? s0[r] : -1e30f; s1[r] = v1 ? s1[r] : -1e30f; }
;   }
;   float mx = fmaxf(s0[0], s1[0]);
; #pragma unroll
;   for (int r = 1; r < 16; ++r) mx = fmaxf(mx, fmaxf(s0[r], s1[r]));
;   mx = fmaxf(mx, __shfl_xor(mx, 32));
;   if (__builtin_amdgcn_ballot_w64(mx > m + 8.0f) != 0ull) {
;     const float mn = fmaxf(m, mx), alpha = fexp2(m - mn);
;     m = mn; l *= alpha;
; #pragma unroll
;     for (int d = 0; d < NDV; ++d) o[d] *= alpha;
;   }
;   float ps = 0.f;
; #pragma unroll
;   for (int r = 0; r < 16; ++r) { s0[r] = fexp2(s0[r] - m); s1[r] = fexp2(s1[r] - m); ps += s0[r] + s1[r]; }
.Lmla_Ys:
	s_nop 15
	s_cmp_lg_u32 s37, s30
	s_cbranch_scc1 .Lmla_Ys_nomask
	v_mov_b32_e32 v253, 0xf149f2ca
	v_sub_u32_e32 v111, v181, v180
	v_cmp_le_i32_e64 s[38:39], 0, v111
	v_cmp_le_i32_e64 s[40:41], 1, v111
	v_cmp_le_i32_e64 s[42:43], 2, v111
	v_cmp_le_i32_e64 s[44:45], 3, v111
	v_cndmask_b32_e64 v80, v253, v80, s[38:39]
	v_cndmask_b32_e64 v81, v253, v81, s[40:41]
	v_cndmask_b32_e64 v82, v253, v82, s[42:43]
	v_cndmask_b32_e64 v83, v253, v83, s[44:45]
	v_cmp_le_i32_e64 s[38:39], 8, v111
	v_cmp_le_i32_e64 s[40:41], 9, v111
	v_cmp_le_i32_e64 s[42:43], 10, v111
	v_cmp_le_i32_e64 s[44:45], 11, v111
	v_cndmask_b32_e64 v84, v253, v84, s[38:39]
	v_cndmask_b32_e64 v85, v253, v85, s[40:41]
	v_cndmask_b32_e64 v86, v253, v86, s[42:43]
	v_cndmask_b32_e64 v87, v253, v87, s[44:45]
	v_cmp_le_i32_e64 s[38:39], 16, v111
	v_cmp_le_i32_e64 s[40:41], 17, v111
	v_cmp_le_i32_e64 s[42:43], 18, v111
	v_cmp_le_i32_e64 s[44:45], 19, v111
	v_cndmask_b32_e64 v88, v253, v88, s[38:39]
	v_cndmask_b32_e64 v89, v253, v89, s[40:41]
	v_cndmask_b32_e64 v90, v253, v90, s[42:43]
	v_cndmask_b32_e64 v91, v253, v91, s[44:45]
	v_cmp_le_i32_e64 s[38:39], 24, v111
	v_cmp_le_i32_e64 s[40:41], 25, v111
	v_cmp_le_i32_e64 s[42:43], 26, v111
	v_cmp_le_i32_e64 s[44:45], 27, v111
	v_cndmask_b32_e64 v92, v253, v92, s[38:39]
	v_cndmask_b32_e64 v93, v253, v93, s[40:41]
	v_cndmask_b32_e64 v94, v253, v94, s[42:43]
	v_cndmask_b32_e64 v95, v253, v95, s[44:45]
.Lmla_Ys_nomask:
	v_max3_f32 v111, v80, v81, v82
	v_max3_f32 v111, v111, v83, v84
	v_max3_f32 v111, v111, v85, v86
	v_max3_f32 v111, v111, v87, v88
	v_max3_f32 v111, v111, v89, v90
	v_max3_f32 v111, v111, v91, v92
	v_max3_f32 v111, v111, v93, v94
	v_max_f32_e32 v111, v111, v95
	s_cmp_ge_u32 s37, s30
	s_cbranch_scc1 .Lmla_Ys_nokpf
	ds_read_b128 v[98:101], v96 offset:12800
	ds_read_b128 v[102:105], v96 offset:12832
	ds_read_b128 v[106:109], v96 offset:12864
.Lmla_Ys_nokpf:
	v_mov_b32_e32 v252, v111
	s_nop 1
	v_permlane32_swap_b32_e32 v111, v252
	s_nop 0
	v_max_f32_e32 v111, v111, v252
	v_mov_b32_e32 v217, v111
	v_sub_f32_e32 v80, v80, v111
	v_sub_f32_e32 v81, v81, v111
	v_sub_f32_e32 v82, v82, v111
	v_sub_f32_e32 v83, v83, v111
	v_sub_f32_e32 v84, v84, v111
	v_sub_f32_e32 v85, v85, v111
	v_sub_f32_e32 v86, v86, v111
	v_sub_f32_e32 v87, v87, v111
	v_sub_f32_e32 v88, v88, v111
	v_sub_f32_e32 v89, v89, v111
	v_sub_f32_e32 v90, v90, v111
	v_sub_f32_e32 v91, v91, v111
	v_sub_f32_e32 v92, v92, v111
	v_sub_f32_e32 v93, v93, v111
	v_sub_f32_e32 v94, v94, v111
	v_sub_f32_e32 v95, v95, v111
	v_xor_b32_e32 v160, 0x80000000, v111
	v_xor_b32_e32 v161, 0x80000000, v111
	v_xor_b32_e32 v162, 0x80000000, v111
	v_xor_b32_e32 v163, 0x80000000, v111
	v_xor_b32_e32 v164, 0x80000000, v111
	v_xor_b32_e32 v165, 0x80000000, v111
	v_xor_b32_e32 v166, 0x80000000, v111
	v_xor_b32_e32 v167, 0x80000000, v111
	v_xor_b32_e32 v168, 0x80000000, v111
	v_xor_b32_e32 v169, 0x80000000, v111
	v_xor_b32_e32 v170, 0x80000000, v111
	v_xor_b32_e32 v171, 0x80000000, v111
	v_xor_b32_e32 v172, 0x80000000, v111
	v_xor_b32_e32 v173, 0x80000000, v111
	v_xor_b32_e32 v174, 0x80000000, v111
	v_xor_b32_e32 v175, 0x80000000, v111
	s_branch .Lmla_s3_done

; #define LAS __attribute__((address_space(3)))
; template <int NQK, int NDV, int KSTR, int VSTR> ...
;     ...
;   const LAS unsigned char* ka = Kt + c * KSTR + h * 16;
;   bf16x8 kc0 = *(const LAS bf16x8*)(ka), kc1 = *(const LAS bf16x8*)(ka + 32 * KSTR);
; #pragma unroll
;   for (int st = 0; st < NQK; ++st) {
;     bf16x8 kn0 = kc0, kn1 = kc1;
;     if (st + 1 < NQK) { kn0 = *(const LAS bf16x8*)(ka + (st + 1) * 32); kn1 = *(const LAS bf16x8*)(ka + 32 * KSTR + (st + 1) * 32); }
;     s0 = mfma32(kc0, qf[st], s0);
;     s1 = mfma32(kc1, qf[st], s1);
;     if (st + 1 < NQK) __builtin_amdgcn_sched_group_barrier(0x100, 2, 0);
;     __builtin_amdgcn_sched_group_barrier(0x008, 2, 0);
;     kc0 = kn0; kc1 = kn1;
;   }
;   if (domask) {
; #pragma unroll
;     for (int r = 0; r < 16; ++r) { const int kp = kpos0 + (r & 3) + 8 * (r >> 2) + 4 * h;
;       const bool v0 = (kp <= qpos) && (kp > qpos - window) && (kp >= 0);
;       const bool v1 = (kp + 32 <= qpos) && (kp + 32 > qpos - window) && (kp + 32 >= 0);
;       s0[r] = v0 ? s0[r] : -1e30f; s1[r] = v1 ? s1[r] : -1e30f; }
;   }
;   float mx = fmaxf(s0[0], s1[0]);
; #pragma unroll
;   for (int r = 1; r < 16; ++r) mx = fmaxf(mx, fmaxf(s0[r], s1[r]));
;   mx = fmaxf(mx, __shfl_xor(mx, 32));
;   if (__builtin_amdgcn_ballot_w64(mx > m + 8.0f) != 0ull) {
;     const float mn = fmaxf(m, mx), alpha = fexp2(m - mn);
;     m = mn; l *= alpha;
; #pragma unroll
;     for (int d = 0; d < NDV; ++d) o[d] *= alpha;
;   }
;   float ps = 0.f;
; #pragma unroll
;   for (int r = 0; r < 16; ++r) { s0[r] = fexp2(s0[r] - m); s1[r] = fexp2(s1[r] - m); ps += s0[r] + s1[r]; }
;   l += ps;
;   bf16x8 pf[4];
; #pragma unroll
;   for (int s = 0; s < 2; ++s) {
;     u32x4 w0, w1;
;     w0.x = pk2(s0[8 * s + 0], s0[8 * s + 1]); w0.y = pk2(s0[8 * s + 2], s0[8 * s + 3]); w0.z = pk2(s0[8 * s + 4], s0[8 * s + 5]); w0.w = pk2(s0[8 * s + 6], s0[8 * s + 7]);
;     w1.x = pk2(s1[8 * s + 0], s1[8 * s + 1]); w1.y = pk2(s1[8 * s + 2], s1[8 * s + 3]); w1.z = pk2(s1[8 * s + 4], s1[8 * s + 5]); w1.w = pk2(s1[8 * s + 6], s1[8 * s + 7]);
;     pf[s] = __builtin_bit_cast(bf16x8, w0); pf[2 + s] = __builtin_bit_cast(bf16x8, w1);
;   }
;   const int i16 = lane & 15, g16 = (lane >> 4) & 1;
;   const LAS unsigned char* va = Vt + (4 * h + (i16 >> 2)) * VSTR + (16 * g16 + 4 * (i16 & 3)) * 2;
;   bf16x8 vc[NDV];
; #pragma unroll
.Lmla_Ype:
	ds_read_b64_tr_b16 v[234:235], v110 offset:15360
	ds_read_b64_tr_b16 v[236:237], v110 offset:17920
	ds_read_b64_tr_b16 v[238:239], v110 offset:15424
	ds_read_b64_tr_b16 v[240:241], v110 offset:17984
	ds_read_b64_tr_b16 v[242:243], v110 offset:15488
	ds_read_b64_tr_b16 v[244:245], v110 offset:18048
	ds_read_b64_tr_b16 v[246:247], v110 offset:15552
	ds_read_b64_tr_b16 v[248:249], v110 offset:18112
	s_waitcnt lgkmcnt(8)
	v_mfma_f32_32x32x16_bf16 v[48:63], v[218:221], v[64:67], v[48:63]
	v_mfma_f32_32x32x16_bf16 v[32:47], v[222:225], v[64:67], v[32:47]
	v_mfma_f32_32x32x16_bf16 v[16:31], v[226:229], v[64:67], v[16:31]
	v_mfma_f32_32x32x16_bf16 v[0:15], v[230:233], v[64:67], v[0:15]
	s_waitcnt lgkmcnt(0)
	v_mfma_f32_32x32x16_bf16 v[48:63], v[234:237], v[68:71], v[48:63]
	v_mfma_f32_32x32x16_bf16 v[32:47], v[238:241], v[68:71], v[32:47]
	v_mfma_f32_32x32x16_bf16 v[16:31], v[242:245], v[68:71], v[16:31]
	v_mfma_f32_32x32x16_bf16 v[0:15], v[246:249], v[68:71], v[0:15]
.Lmla_s3_done:
	v_add3_u32 v110, s34, v202, v203
	s_add_u32 s37, s31, 1
	s_cmp_le_u32 s37, s30
	s_cbranch_scc0 .Lmla_s4_tail
.Lmla_Xfo:
	s_waitcnt lgkmcnt(2)
	v_mfma_f32_32x32x16_bf16 v[64:79], v[98:101], v[112:115], v[160:175]
	ds_read_b128 v[98:101], v96 offset:12896
	v_exp_f32_e32 v80, v80
	v_exp_f32_e32 v81, v81
	v_exp_f32_e32 v82, v82
	v_exp_f32_e32 v83, v83
	s_waitcnt lgkmcnt(2)
	v_mfma_f32_32x32x16_bf16 v[64:79], v[102:105], v[116:119], v[64:79]
	ds_read_b128 v[102:105], v96 offset:12928
	v_add_f32_e32 v252, v80, v81
	v_exp_f32_e32 v84, v84
	v_exp_f32_e32 v85, v85
	v_add_f32_e32 v253, v82, v83
	s_waitcnt lgkmcnt(2)
	v_mfma_f32_32x32x16_bf16 v[64:79], v[106:109], v[120:123], v[64:79]
	ds_read_b128 v[106:109], v96 offset:12960
	v_cvt_pk_bf16_f32 v80, v80, v81
	v_exp_f32_e32 v86, v86
	v_exp_f32_e32 v87, v87
	v_add_f32_e32 v252, v252, v84
	s_waitcnt lgkmcnt(2)
	v_mfma_f32_32x32x16_bf16 v[64:79], v[98:101], v[124:127], v[64:79]
	ds_read_b128 v[98:101], v96 offset:12992
	v_add_f32_e32 v252, v252, v85
	v_cvt_pk_bf16_f32 v81, v82, v83
	v_exp_f32_e32 v88, v88
	v_exp_f32_e32 v89, v89
	s_waitcnt lgkmcnt(2)
	v_mfma_f32_32x32x16_bf16 v[64:79], v[102:105], v[128:131], v[64:79]
	ds_read_b128 v[102:105], v96 offset:13024
	v_add_f32_e32 v253, v253, v86
	v_add_f32_e32 v253, v253, v87
	v_cvt_pk_bf16_f32 v82, v84, v85
	v_exp_f32_e32 v90, v90
	s_waitcnt lgkmcnt(2)
	v_mfma_f32_32x32x16_bf16 v[64:79], v[106:109], v[132:135], v[64:79]
	ds_read_b128 v[106:109], v96 offset:13056
	v_exp_f32_e32 v91, v91
	v_add_f32_e32 v252, v252, v88
	v_add_f32_e32 v252, v252, v89
	s_waitcnt lgkmcnt(2)
	v_mfma_f32_32x32x16_bf16 v[64:79], v[98:101], v[136:139], v[64:79]
	ds_read_b128 v[98:101], v96 offset:13088
	v_cvt_pk_bf16_f32 v83, v86, v87
	v_exp_f32_e32 v92, v92
	v_exp_f32_e32 v93, v93
	s_waitcnt lgkmcnt(2)
	v_mfma_f32_32x32x16_bf16 v[64:79], v[102:105], v[140:143], v[64:79]
	ds_read_b128 v[102:105], v96 offset:13120
	v_add_f32_e32 v253, v253, v90
	v_add_f32_e32 v253, v253, v91
	v_cvt_pk_bf16_f32 v84, v88, v89
	s_waitcnt lgkmcnt(2)
	v_mfma_f32_32x32x16_bf16 v[64:79], v[106:109], v[144:147], v[64:79]
	ds_read_b128 v[106:109], v96 offset:13152
	ds_read_b64_tr_b16 v[218:219], v110 offset:0
	ds_read_b64_tr_b16 v[220:221], v110 offset:2560
	ds_read_b64_tr_b16 v[222:223], v110 offset:64
	ds_read_b64_tr_b16 v[224:225], v110 offset:2624
	ds_read_b64_tr_b16 v[226:227], v110 offset:128
	ds_read_b64_tr_b16 v[228:229], v110 offset:2688
	ds_read_b64_tr_b16 v[230:231], v110 offset:192
	ds_read_b64_tr_b16 v[232:233], v110 offset:2752
	v_exp_f32_e32 v94, v94
	v_exp_f32_e32 v95, v95
	v_add_f32_e32 v252, v252, v92
	s_waitcnt lgkmcnt(10)
	v_mfma_f32_32x32x16_bf16 v[64:79], v[98:101], v[148:151], v[64:79]
	v_add_f32_e32 v252, v252, v93
	v_cvt_pk_bf16_f32 v85, v90, v91
	s_nop 0
	s_waitcnt lgkmcnt(9)
	v_mfma_f32_32x32x16_bf16 v[64:79], v[102:105], v[152:155], v[64:79]
	v_add_f32_e32 v253, v253, v94
	v_add_f32_e32 v253, v253, v95
	v_cvt_pk_bf16_f32 v86, v92, v93
	s_waitcnt lgkmcnt(8)
	v_mfma_f32_32x32x16_bf16 v[64:79], v[106:109], v[156:159], v[64:79]
	v_cvt_pk_bf16_f32 v87, v94, v95
	v_add_f32_e32 v252, v252, v253
	v_add_f32_e32 v216, v216, v252
	s_branch .Lmla_s4_done
.Lmla_s4_tail:
	s_add_u32 s47, s30, 1
	s_cmp_eq_u32 s37, s47
	s_cbranch_scc0 .Lmla_s4_done
.Lmla_Xso:
	v_exp_f32_e32 v80, v80
	v_exp_f32_e32 v81, v81
	v_exp_f32_e32 v82, v82
	v_exp_f32_e32 v83, v83
	v_add_f32_e32 v252, v80, v81
	v_exp_f32_e32 v84, v84
	v_exp_f32_e32 v85, v85
	v_add_f32_e32 v253, v82, v83
	v_cvt_pk_bf16_f32 v80, v80, v81
	v_exp_f32_e32 v86, v86
	v_exp_f32_e32 v87, v87
	v_add_f32_e32 v252, v252, v84
	v_add_f32_e32 v252, v252, v85
	v_cvt_pk_bf16_f32 v81, v82, v83
	v_exp_f32_e32 v88, v88
	v_exp_f32_e32 v89, v89
	v_add_f32_e32 v253, v253, v86
	v_add_f32_e32 v253, v253, v87
	v_cvt_pk_bf16_f32 v82, v84, v85
	v_exp_f32_e32 v90, v90
	v_exp_f32_e32 v91, v91
	v_add_f32_e32 v252, v252, v88
	v_add_f32_e32 v252, v252, v89
	v_cvt_pk_bf16_f32 v83, v86, v87
	v_exp_f32_e32 v92, v92
	v_exp_f32_e32 v93, v93
	v_add_f32_e32 v253, v253, v90
	v_add_f32_e32 v253, v253, v91
	v_cvt_pk_bf16_f32 v84, v88, v89
	v_exp_f32_e32 v94, v94
	v_exp_f32_e32 v95, v95
	v_add_f32_e32 v252, v252, v92
	v_add_f32_e32 v252, v252, v93
	v_cvt_pk_bf16_f32 v85, v90, v91
	s_nop 0
	v_add_f32_e32 v253, v253, v94
	v_add_f32_e32 v253, v253, v95
	v_cvt_pk_bf16_f32 v86, v92, v93
	v_cvt_pk_bf16_f32 v87, v94, v95
	v_add_f32_e32 v252, v252, v253
	v_add_f32_e32 v216, v216, v252
	ds_read_b64_tr_b16 v[218:219], v110 offset:0
	ds_read_b64_tr_b16 v[220:221], v110 offset:2560
	ds_read_b64_tr_b16 v[222:223], v110 offset:64
	ds_read_b64_tr_b16 v[224:225], v110 offset:2624
	ds_read_b64_tr_b16 v[226:227], v110 offset:128
	ds_read_b64_tr_b16 v[228:229], v110 offset:2688
	ds_read_b64_tr_b16 v[230:231], v110 offset:192
	ds_read_b64_tr_b16 v[232:233], v110 offset:2752
; #define LAS __attribute__((address_space(3)))
; __device__ __forceinline__ float fexp2(float x) { return __builtin_amdgcn_exp2f(x); }
; template <int NQK, int NDV, int KSTR, int VSTR> ...
;     ...
;   if (__builtin_amdgcn_ballot_w64(mx > m + 8.0f) != 0ull) {
;     const float mn = fmaxf(m, mx), alpha = fexp2(m - mn);
;     m = mn; l *= alpha;
; #pragma unroll
;     for (int d = 0; d < NDV; ++d) o[d] *= alpha;
;   }
; __device__ __forceinline__ void mla_phase(KP p, LAS unsigned char* lds, int wv0) {
;     ...
;     for (int kt = 0; kt < ntiles; ++kt) {
;       LAS unsigned char* Kb = lds + (kt & 1) * KB; LAS unsigned char* Vb = lds + 2 * KB + (kt & 1) * VB;
;       *(LAS u32x4*)(Kb + kdst[0]) = kr0; *(LAS u32x4*)(Kb + kdst[1]) = kr1; *(LAS u32x4*)(Kb + kdst[2]) = kr2;
;       *(LAS u32x4*)(Vb + vdst[0]) = vr0; *(LAS u32x4*)(Vb + vdst[1]) = vr1;
;       __syncthreads();
;       if (kt + 1 < ntiles) {
;         ksrc[0] += k0rope ? kinc1 : kinc0; ksrc[1] += k1rope ? kinc1 : kinc0; ksrc[2] += k2rope ? kinc1 : kinc0; vsrc[0] += kinc0; vsrc[1] += kinc0;
;         kr0 = *(const u32x4*)(wsb + ksrc[0]); kr1 = *(const u32x4*)(wsb + ksrc[1]); kr2 = *(const u32x4*)(wsb + ksrc[2]); vr0 = *(const u32x4*)(wsb + vsrc[0]); vr1 = *(const u32x4*)(wsb + vsrc[1]);
;       }
;       const int k0 = kt * 64;
;       if (k0 <= q0 + 31) attn_tile<12, 4, KSTR, VSTR>(qf, o, m, l, Kb, Vb, lane, q0 + c, k0, 1 << 30, k0 + 63 > q0);
;     }
.Lmla_s4_done:
	s_mov_b32 s35, s34
	s_mov_b32 s34, s36
	s_add_u32 s36, s36, 0x5000
	s_cmp_eq_u32 s36, 0x1b800
	s_cselect_b32 s36, 0xc800, s36
	s_xor_b32 s32, s32, 0x6400
	s_add_u32 s28, s28, 1
	s_cmp_le_u32 s28, s29
	s_cbranch_scc1 .Lmla_iter
	s_branch .LBB0_821
.Lmla_rescale1:
	s_nop 15
	s_nop 7
	v_max_f32_e32 v111, 0, v111
	v_sub_f32_e32 v252, 0, v111
	v_add_f32_e32 v217, v217, v111
	v_exp_f32_e32 v252, v252
	v_sub_f32_e32 v64, v64, v111
	v_sub_f32_e32 v65, v65, v111
	v_sub_f32_e32 v66, v66, v111
	v_sub_f32_e32 v67, v67, v111
	v_sub_f32_e32 v68, v68, v111
	v_sub_f32_e32 v69, v69, v111
	v_sub_f32_e32 v70, v70, v111
	v_sub_f32_e32 v71, v71, v111
	v_sub_f32_e32 v72, v72, v111
	v_sub_f32_e32 v73, v73, v111
	v_sub_f32_e32 v74, v74, v111
	v_sub_f32_e32 v75, v75, v111
	v_sub_f32_e32 v76, v76, v111
	v_sub_f32_e32 v77, v77, v111
	v_sub_f32_e32 v78, v78, v111
	v_sub_f32_e32 v79, v79, v111
	v_mul_f32_e32 v216, v216, v252
	v_pk_mul_f32 v[0:1], v[0:1], v[252:253] op_sel_hi:[1,0]
	v_pk_mul_f32 v[2:3], v[2:3], v[252:253] op_sel_hi:[1,0]
	v_pk_mul_f32 v[4:5], v[4:5], v[252:253] op_sel_hi:[1,0]
	v_pk_mul_f32 v[6:7], v[6:7], v[252:253] op_sel_hi:[1,0]
	v_pk_mul_f32 v[8:9], v[8:9], v[252:253] op_sel_hi:[1,0]
	v_pk_mul_f32 v[10:11], v[10:11], v[252:253] op_sel_hi:[1,0]
	v_pk_mul_f32 v[12:13], v[12:13], v[252:253] op_sel_hi:[1,0]
	v_pk_mul_f32 v[14:15], v[14:15], v[252:253] op_sel_hi:[1,0]
	v_pk_mul_f32 v[16:17], v[16:17], v[252:253] op_sel_hi:[1,0]
	v_pk_mul_f32 v[18:19], v[18:19], v[252:253] op_sel_hi:[1,0]
	v_pk_mul_f32 v[20:21], v[20:21], v[252:253] op_sel_hi:[1,0]
	v_pk_mul_f32 v[22:23], v[22:23], v[252:253] op_sel_hi:[1,0]
	v_pk_mul_f32 v[24:25], v[24:25], v[252:253] op_sel_hi:[1,0]
	v_pk_mul_f32 v[26:27], v[26:27], v[252:253] op_sel_hi:[1,0]
	v_pk_mul_f32 v[28:29], v[28:29], v[252:253] op_sel_hi:[1,0]
	v_pk_mul_f32 v[30:31], v[30:31], v[252:253] op_sel_hi:[1,0]
	v_pk_mul_f32 v[32:33], v[32:33], v[252:253] op_sel_hi:[1,0]
	v_pk_mul_f32 v[34:35], v[34:35], v[252:253] op_sel_hi:[1,0]
	v_pk_mul_f32 v[36:37], v[36:37], v[252:253] op_sel_hi:[1,0]
	v_pk_mul_f32 v[38:39], v[38:39], v[252:253] op_sel_hi:[1,0]
	v_pk_mul_f32 v[40:41], v[40:41], v[252:253] op_sel_hi:[1,0]
	v_pk_mul_f32 v[42:43], v[42:43], v[252:253] op_sel_hi:[1,0]
	v_pk_mul_f32 v[44:45], v[44:45], v[252:253] op_sel_hi:[1,0]
	v_pk_mul_f32 v[46:47], v[46:47], v[252:253] op_sel_hi:[1,0]
	v_pk_mul_f32 v[48:49], v[48:49], v[252:253] op_sel_hi:[1,0]
	v_pk_mul_f32 v[50:51], v[50:51], v[252:253] op_sel_hi:[1,0]
	v_pk_mul_f32 v[52:53], v[52:53], v[252:253] op_sel_hi:[1,0]
	v_pk_mul_f32 v[54:55], v[54:55], v[252:253] op_sel_hi:[1,0]
	v_pk_mul_f32 v[56:57], v[56:57], v[252:253] op_sel_hi:[1,0]
	v_pk_mul_f32 v[58:59], v[58:59], v[252:253] op_sel_hi:[1,0]
	v_pk_mul_f32 v[60:61], v[60:61], v[252:253] op_sel_hi:[1,0]
	v_pk_mul_f32 v[62:63], v[62:63], v[252:253] op_sel_hi:[1,0]
	v_xor_b32_e32 v160, 0x80000000, v217
	v_xor_b32_e32 v161, 0x80000000, v217
	v_xor_b32_e32 v162, 0x80000000, v217
	v_xor_b32_e32 v163, 0x80000000, v217
	v_xor_b32_e32 v164, 0x80000000, v217
	v_xor_b32_e32 v165, 0x80000000, v217
	v_xor_b32_e32 v166, 0x80000000, v217
	v_xor_b32_e32 v167, 0x80000000, v217
	v_xor_b32_e32 v168, 0x80000000, v217
	v_xor_b32_e32 v169, 0x80000000, v217
	v_xor_b32_e32 v170, 0x80000000, v217
	v_xor_b32_e32 v171, 0x80000000, v217
	v_xor_b32_e32 v172, 0x80000000, v217
	v_xor_b32_e32 v173, 0x80000000, v217
	v_xor_b32_e32 v174, 0x80000000, v217
	v_xor_b32_e32 v175, 0x80000000, v217
	s_branch .Lmla_ret0
; #define LAS __attribute__((address_space(3)))
; __device__ __forceinline__ int otid(int wv0) { int t = (wv0 << 6) | olane(); asm volatile("" : "+v"(t)); return t; }
; __device__ __forceinline__ float fexp2(float x) { return __builtin_amdgcn_exp2f(x); }
; __device__ __forceinline__ unsigned xb_add(unsigned* p, unsigned v) { return __hip_atomic_fetch_add(p, v, __ATOMIC_RELAXED, __HIP_MEMORY_SCOPE_AGENT); }
; __device__ __forceinline__ unsigned xb_xcc_id() { return (unsigned)__builtin_amdgcn_s_getreg((3 << 11) | 20) & 0xFu; }
; template <int NQK, int NDV, int KSTR, int VSTR> ...
;     ...
;   if (__builtin_amdgcn_ballot_w64(mx > m + 8.0f) != 0ull) {
;     const float mn = fmaxf(m, mx), alpha = fexp2(m - mn);
;     m = mn; l *= alpha;
; #pragma unroll
;     for (int d = 0; d < NDV; ++d) o[d] *= alpha;
;   }
; __device__ __forceinline__ void xcd_barrier(unsigned* bar, volatile LAS unsigned* st, int wv0) {
;     asm volatile("s_waitcnt vmcnt(0)" ::: "memory");
;     __syncthreads();
;     if (otid(wv0) == 0) {
;         const unsigned x = xb_xcc_id();
;         __builtin_amdgcn_s_waitcnt(0);
;         unsigned nloc = st[0], nx = st[1];
;         if (nloc == 0u) { xcd_barrier_complete(bar, x, nloc, nx); st[0] = nloc; st[1] = nx; }
;         const unsigned old = xb_add(&bar[XB_XSUB(x)], 1u);
.Lmla_rescale0:
	s_nop 15
	s_nop 7
	v_max_f32_e32 v111, 0, v111
	v_sub_f32_e32 v252, 0, v111
	v_add_f32_e32 v217, v217, v111
	v_exp_f32_e32 v252, v252
	v_sub_f32_e32 v80, v80, v111
	v_sub_f32_e32 v81, v81, v111
	v_sub_f32_e32 v82, v82, v111
	v_sub_f32_e32 v83, v83, v111
	v_sub_f32_e32 v84, v84, v111
	v_sub_f32_e32 v85, v85, v111
	v_sub_f32_e32 v86, v86, v111
	v_sub_f32_e32 v87, v87, v111
	v_sub_f32_e32 v88, v88, v111
	v_sub_f32_e32 v89, v89, v111
	v_sub_f32_e32 v90, v90, v111
	v_sub_f32_e32 v91, v91, v111
	v_sub_f32_e32 v92, v92, v111
	v_sub_f32_e32 v93, v93, v111
	v_sub_f32_e32 v94, v94, v111
	v_sub_f32_e32 v95, v95, v111
	v_mul_f32_e32 v216, v216, v252
	v_pk_mul_f32 v[0:1], v[0:1], v[252:253] op_sel_hi:[1,0]
	v_pk_mul_f32 v[2:3], v[2:3], v[252:253] op_sel_hi:[1,0]
	v_pk_mul_f32 v[4:5], v[4:5], v[252:253] op_sel_hi:[1,0]
	v_pk_mul_f32 v[6:7], v[6:7], v[252:253] op_sel_hi:[1,0]
	v_pk_mul_f32 v[8:9], v[8:9], v[252:253] op_sel_hi:[1,0]
	v_pk_mul_f32 v[10:11], v[10:11], v[252:253] op_sel_hi:[1,0]
	v_pk_mul_f32 v[12:13], v[12:13], v[252:253] op_sel_hi:[1,0]
	v_pk_mul_f32 v[14:15], v[14:15], v[252:253] op_sel_hi:[1,0]
	v_pk_mul_f32 v[16:17], v[16:17], v[252:253] op_sel_hi:[1,0]
	v_pk_mul_f32 v[18:19], v[18:19], v[252:253] op_sel_hi:[1,0]
	v_pk_mul_f32 v[20:21], v[20:21], v[252:253] op_sel_hi:[1,0]
	v_pk_mul_f32 v[22:23], v[22:23], v[252:253] op_sel_hi:[1,0]
	v_pk_mul_f32 v[24:25], v[24:25], v[252:253] op_sel_hi:[1,0]
	v_pk_mul_f32 v[26:27], v[26:27], v[252:253] op_sel_hi:[1,0]
	v_pk_mul_f32 v[28:29], v[28:29], v[252:253] op_sel_hi:[1,0]
	v_pk_mul_f32 v[30:31], v[30:31], v[252:253] op_sel_hi:[1,0]
	v_pk_mul_f32 v[32:33], v[32:33], v[252:253] op_sel_hi:[1,0]
	v_pk_mul_f32 v[34:35], v[34:35], v[252:253] op_sel_hi:[1,0]
	v_pk_mul_f32 v[36:37], v[36:37], v[252:253] op_sel_hi:[1,0]
	v_pk_mul_f32 v[38:39], v[38:39], v[252:253] op_sel_hi:[1,0]
	v_pk_mul_f32 v[40:41], v[40:41], v[252:253] op_sel_hi:[1,0]
	v_pk_mul_f32 v[42:43], v[42:43], v[252:253] op_sel_hi:[1,0]
	v_pk_mul_f32 v[44:45], v[44:45], v[252:253] op_sel_hi:[1,0]
	v_pk_mul_f32 v[46:47], v[46:47], v[252:253] op_sel_hi:[1,0]
	v_pk_mul_f32 v[48:49], v[48:49], v[252:253] op_sel_hi:[1,0]
	v_pk_mul_f32 v[50:51], v[50:51], v[252:253] op_sel_hi:[1,0]
	v_pk_mul_f32 v[52:53], v[52:53], v[252:253] op_sel_hi:[1,0]
	v_pk_mul_f32 v[54:55], v[54:55], v[252:253] op_sel_hi:[1,0]
	v_pk_mul_f32 v[56:57], v[56:57], v[252:253] op_sel_hi:[1,0]
	v_pk_mul_f32 v[58:59], v[58:59], v[252:253] op_sel_hi:[1,0]
	v_pk_mul_f32 v[60:61], v[60:61], v[252:253] op_sel_hi:[1,0]
	v_pk_mul_f32 v[62:63], v[62:63], v[252:253] op_sel_hi:[1,0]
	v_xor_b32_e32 v160, 0x80000000, v217
	v_xor_b32_e32 v161, 0x80000000, v217
	v_xor_b32_e32 v162, 0x80000000, v217
	v_xor_b32_e32 v163, 0x80000000, v217
	v_xor_b32_e32 v164, 0x80000000, v217
	v_xor_b32_e32 v165, 0x80000000, v217
	v_xor_b32_e32 v166, 0x80000000, v217
	v_xor_b32_e32 v167, 0x80000000, v217
	v_xor_b32_e32 v168, 0x80000000, v217
	v_xor_b32_e32 v169, 0x80000000, v217
	v_xor_b32_e32 v170, 0x80000000, v217
	v_xor_b32_e32 v171, 0x80000000, v217
	v_xor_b32_e32 v172, 0x80000000, v217
	v_xor_b32_e32 v173, 0x80000000, v217
	v_xor_b32_e32 v174, 0x80000000, v217
	v_xor_b32_e32 v175, 0x80000000, v217
	s_branch .Lmla_ret1
.LBB0_846:
	v_mov_b32_e32 v228, 0x1ff
	v_mov_b32_e32 v229, 0
	v_mov_b32_e32 v231, 0x2000
	v_mov_b32_e32 v244, 0x200
	v_mov_b32_e32 v245, 0
	v_mov_b32_e32 v246, 0x3727c5ac
	v_mov_b32_e32 v247, 0xf149f2ca
	s_mov_b32 s0, -1
	s_waitcnt vmcnt(0)
	s_barrier
	s_nop 0
	v_mbcnt_lo_u32_b32 v0, s0, 0
	v_mbcnt_hi_u32_b32 v0, s0, v0
	v_or_b32_e32 v0, s16, v0
	s_nop 0
	v_cmp_eq_u32_e32 vcc, 0, v0
	s_and_saveexec_b64 s[0:1], vcc
	s_xor_b64 s[2:3], exec, s[0:1]
	s_cbranch_execz .LBB0_899
	s_add_i32 s1, 0, 0x20000
	v_mov_b32_e32 v0, s1
	s_load_dwordx2 s[4:5], s[54:55], 0xd0
	s_getreg_b32 s0, hwreg(HW_REG_XCC_ID, 0, 4)
	s_waitcnt vmcnt(0) expcnt(0) lgkmcnt(0)
	ds_read_b32 v2, v0
	v_mov_b32_e32 v0, s76
	ds_read_b32 v0, v0
	s_and_b32 s0, s0, 15
	s_waitcnt lgkmcnt(1)
	v_cmp_ne_u32_e32 vcc, 0, v2
	s_cbranch_vccnz .LBB0_862
	s_add_u32 s6, s4, 0x27740200
	s_addc_u32 s7, s5, 0
	s_add_u32 s8, s4, 0x27740400
	s_addc_u32 s9, s5, 0
	s_add_u32 s10, s4, 0x27740500
	s_addc_u32 s11, s5, 0
	s_add_u32 s12, s4, 0x27740600
	s_addc_u32 s13, s5, 0
	s_add_u32 s14, s4, 0x27740700
	s_addc_u32 s15, s5, 0
	s_add_u32 s16, s4, 0x27740800
	s_addc_u32 s17, s5, 0
	s_add_u32 s18, s4, 0x27740900
	s_addc_u32 s19, s5, 0
	s_add_u32 s20, s4, 0x27740a00
	s_addc_u32 s21, s5, 0
	s_add_u32 s22, s4, 0x27740b00
	s_addc_u32 s23, s5, 0
	s_add_u32 s24, s4, 0x27740c00
	s_addc_u32 s25, s5, 0
	s_add_u32 s26, s4, 0x27740d00
	s_addc_u32 s27, s5, 0
	s_add_u32 s28, s4, 0x27740e00
	s_addc_u32 s29, s5, 0
	s_add_u32 s30, s4, 0x27740f00
	s_addc_u32 s31, s5, 0
	s_add_u32 s34, s4, 0x27741000
	s_addc_u32 s35, s5, 0
	s_add_u32 s36, s4, 0x27741100
	s_addc_u32 s37, s5, 0
	s_add_u32 s38, s4, 0x27741200
	s_addc_u32 s39, s5, 0
	s_add_u32 s40, s4, 0x27741300
	s_addc_u32 s41, s5, 0
	s_mov_b32 s48, 1
	s_branch .LBB0_850
